# pool mixer: sliding-window section specialized per group (window width w = 2<<g resolved once per unit instead of ~70 wave-uniform branches per unit)
# speedup vs baseline: 1.0062x; 1.0044x over previous
; __device__ __forceinline__ unsigned cvt_pk_bf16(float lo, float hi) { unsigned r; asm volatile("v_cvt_pk_bf16_f32 %0, %1, %2" : "=v"(r) : "v"(lo), "v"(hi)); return r; }
; #define LAS __attribute__((address_space(3)))
; __device__ __forceinline__ float bf_lo(unsigned u) { return __uint_as_float(u << 16); }
; __device__ __forceinline__ float bf_hi(unsigned u) { return __uint_as_float(u & 0xffff0000u); }
; __device__ __forceinline__ void pool_phase(LAS unsigned char* lds, const bf16_t* PROJ, const bf16_t* PW, const float* pscale, bf16_t* Y, float* SS, int bx, int G) {
;     ...
;             unsigned xr[31];
; #pragma unroll
;             for (int r = 0; r < 31; ++r) xr[r] = xs[(t_start + r + 1) * 128];
;             float s0 = 0.f, s1 = 0.f;
; #pragma unroll
;             for (int j = 1; j < 16; ++j) if (j < w) { s0 += bf_lo(xr[15 - j]); s1 += bf_hi(xr[15 - j]); }
; #pragma unroll
;             for (int tt = 0; tt < 16; ++tt) { const int t = t_start + tt; const unsigned x = xr[tt + 15]; const float x0 = bf_lo(x), x1 = bf_hi(x);
;                 s0 += x0; s1 += x1; const int pos = pos0 + t; const float rc = __builtin_amdgcn_rcpf((float)((pos + 1 < w) ? (pos + 1) : w));
;                 const float d0 = s0 * rc - x0, d1 = s1 * rc - x1;
;                 *(LAS unsigned*)(lds + PL_DT + t * PL_DROW + cp * 4) = cvt_pk_bf16(d0, d1);
;                 const unsigned xo = (w == 2) ? xr[tt + 14] : (w == 4) ? xr[tt + 12] : (w == 8) ? xr[tt + 8] : xr[tt]; s0 -= bf_lo(xo); s1 -= bf_hi(xo); }
.LBB0_484:
	s_cmp_eq_u32 s74, 0
	s_cbranch_scc1 .Lpool_g0
	s_cmp_eq_u32 s74, 1
	s_cbranch_scc1 .Lpool_g1
	s_cmp_eq_u32 s74, 2
	s_cbranch_scc1 .Lpool_g2
	ds_read2st64_b32 v[124:125], v188 offset0:2 offset1:4
	ds_read2st64_b32 v[136:137], v188 offset0:6 offset1:8
	ds_read2st64_b32 v[140:141], v188 offset0:10 offset1:12
	ds_read2st64_b32 v[138:139], v188 offset0:14 offset1:16
	ds_read2st64_b32 v[122:123], v188 offset0:18 offset1:20
	ds_read2st64_b32 v[116:117], v188 offset0:22 offset1:24
	ds_read2st64_b32 v[110:111], v188 offset0:26 offset1:28
	ds_read2st64_b32 v[154:155], v188 offset0:30 offset1:34
	ds_read_b32 v181, v189 offset:512
	ds_read2st64_b32 v[152:153], v188 offset0:36 offset1:38
	ds_read2st64_b32 v[150:151], v188 offset0:40 offset1:42
	ds_read2st64_b32 v[126:127], v188 offset0:44 offset1:46
	ds_read2st64_b32 v[118:119], v188 offset0:48 offset1:50
	ds_read2st64_b32 v[114:115], v188 offset0:52 offset1:54
	ds_read2st64_b32 v[108:109], v188 offset0:56 offset1:58
	ds_read2st64_b32 v[102:103], v188 offset0:60 offset1:62
	s_waitcnt lgkmcnt(8)
	v_lshlrev_b32_e32 v105, 16, v154
	v_and_b32_e32 v104, 0xffff0000, v154
	v_add_f32_e32 v112, 0, v105
	v_add_f32_e32 v113, 0, v104
	v_lshlrev_b32_e32 v107, 16, v111
	v_and_b32_e32 v106, 0xffff0000, v111
	v_add_f32_e32 v120, v112, v107
	v_add_f32_e32 v121, v113, v106
	v_lshlrev_b32_e32 v111, 16, v110
	v_and_b32_e32 v110, 0xffff0000, v110
	s_add_i32 s88, s76, s79
	v_add_f32_e32 v120, v120, v111
	v_add_f32_e32 v121, v121, v110
	s_ashr_i32 s70, s88, 31
	v_cndmask_b32_e64 v128, v121, v113, s[10:11]
	v_cndmask_b32_e64 v129, v120, v112, s[10:11]
	v_lshlrev_b32_e32 v113, 16, v117
	v_and_b32_e32 v112, 0xffff0000, v117
	s_lshr_b32 s70, s70, 20
	v_add_f32_e32 v120, v129, v113
	v_add_f32_e32 v121, v128, v112
	v_lshlrev_b32_e32 v117, 16, v116
	v_and_b32_e32 v116, 0xffff0000, v116
	s_add_i32 s70, s88, s70
	v_add_f32_e32 v142, v120, v117
	v_add_f32_e32 v143, v121, v116
	v_lshlrev_b32_e32 v121, 16, v123
	v_and_b32_e32 v120, 0xffff0000, v123
	s_and_b32 s70, s70, 0xfffff000
	v_add_f32_e32 v142, v142, v121
	v_add_f32_e32 v143, v143, v120
	v_lshlrev_b32_e32 v123, 16, v122
	v_and_b32_e32 v122, 0xffff0000, v122
	s_sub_i32 s70, s88, s70
	v_add_f32_e32 v142, v142, v123
	v_add_f32_e32 v143, v143, v122
	v_cndmask_b32_e64 v154, v128, v143, s[12:13]
	v_cndmask_b32_e64 v195, v129, v142, s[12:13]
	v_lshlrev_b32_e32 v129, 16, v139
	v_and_b32_e32 v128, 0xffff0000, v139
	s_or_b32 s72, s70, 1
	v_lshlrev_b32_e32 v139, 16, v138
	v_and_b32_e32 v138, 0xffff0000, v138
	v_lshlrev_b32_e32 v143, 16, v141
	v_and_b32_e32 v142, 0xffff0000, v141
	v_lshlrev_b32_e32 v149, 16, v140
	v_and_b32_e32 v148, 0xffff0000, v140
	v_lshlrev_b32_e32 v147, 16, v137
	v_and_b32_e32 v146, 0xffff0000, v137
	v_lshlrev_b32_e32 v145, 16, v136
	v_and_b32_e32 v144, 0xffff0000, v136
	v_lshlrev_b32_e32 v141, 16, v125
	v_and_b32_e32 v140, 0xffff0000, v125
	v_lshlrev_b32_e32 v137, 16, v124
	v_and_b32_e32 v136, 0xffff0000, v124
	s_waitcnt lgkmcnt(7)
	v_lshlrev_b32_e32 v125, 16, v181
	v_and_b32_e32 v124, 0xffff0000, v181
	v_add_f32_e32 v181, v195, v129
	v_add_f32_e32 v196, v154, v128
	v_add_u32_e32 v197, s72, v1
	v_add_f32_e32 v181, v181, v139
	v_add_f32_e32 v196, v196, v138
	v_min_i32_e32 v197, s78, v197
	v_add_f32_e32 v181, v181, v143
	v_add_f32_e32 v196, v196, v142
	v_cvt_f32_i32_e32 v197, v197
	v_add_f32_e32 v181, v181, v149
	v_add_f32_e32 v196, v196, v148
	v_add_f32_e32 v181, v181, v147
	v_add_f32_e32 v196, v196, v146
	v_add_f32_e32 v181, v181, v145
	v_add_f32_e32 v196, v196, v144
	v_add_f32_e32 v181, v181, v141
	v_add_f32_e32 v196, v196, v140
	v_rcp_iflag_f32_e32 v197, v197
	v_add_f32_e32 v181, v181, v137
	v_add_f32_e32 v196, v196, v136
	v_cndmask_b32_e64 v196, v154, v196, s[14:15]
	v_cndmask_b32_e64 v154, v195, v181, s[14:15]
	v_add_f32_e32 v154, v154, v125
	v_add_f32_e32 v195, v196, v124
	v_fma_f32 v181, v197, v154, -v125
	v_fma_f32 v196, v197, v195, -v124
	v_cvt_pk_bf16_f32 v181, v181, v196
	ds_write_b32 v194, v181 offset:40960
	v_add_u32_e32 v181, s72, v160
	v_min_i32_e32 v181, s78, v181
	v_cvt_f32_i32_e32 v181, v181
	v_sub_f32_e32 v154, v154, v137
	v_sub_f32_e32 v195, v195, v136
	v_lshlrev_b32_e32 v137, 16, v155
	v_rcp_iflag_f32_e32 v181, v181
	v_and_b32_e32 v136, 0xffff0000, v155
	v_add_f32_e32 v154, v154, v137
	v_add_f32_e32 v155, v195, v136
	v_fma_f32 v195, v181, v154, -v137
	v_fma_f32 v181, v181, v155, -v136
	v_cvt_pk_bf16_f32 v181, v195, v181
	ds_write_b32 v194, v181 offset:41488
	v_add_u32_e32 v181, s72, v161
	v_min_i32_e32 v181, s78, v181
	v_cvt_f32_i32_e32 v181, v181
	v_sub_f32_e32 v154, v154, v141
	s_waitcnt lgkmcnt(8)
	v_lshlrev_b32_e32 v141, 16, v152
	v_sub_f32_e32 v155, v155, v140
	v_rcp_iflag_f32_e32 v181, v181
	v_and_b32_e32 v140, 0xffff0000, v152
	v_add_f32_e32 v152, v154, v141
	v_add_f32_e32 v154, v155, v140
	v_fma_f32 v155, v181, v152, -v141
	v_fma_f32 v181, v181, v154, -v140
	v_cvt_pk_bf16_f32 v155, v155, v181
	ds_write_b32 v194, v155 offset:42016
	v_add_u32_e32 v155, s72, v162
	v_min_i32_e32 v155, s78, v155
	v_cvt_f32_i32_e32 v155, v155
	v_sub_f32_e32 v152, v152, v145
	v_lshlrev_b32_e32 v145, 16, v153
	v_sub_f32_e32 v154, v154, v144
	v_rcp_iflag_f32_e32 v155, v155
	v_and_b32_e32 v144, 0xffff0000, v153
	v_add_f32_e32 v152, v152, v145
	v_add_f32_e32 v153, v154, v144
	v_fma_f32 v154, v155, v152, -v145
	v_fma_f32 v155, v155, v153, -v144
	v_cvt_pk_bf16_f32 v154, v154, v155
	ds_write_b32 v194, v154 offset:42544
	v_add_u32_e32 v154, s72, v163
	v_min_i32_e32 v154, s78, v154
	v_cvt_f32_i32_e32 v154, v154
	v_sub_f32_e32 v152, v152, v147
	s_waitcnt lgkmcnt(9)
; __device__ __forceinline__ unsigned cvt_pk_bf16(float lo, float hi) { unsigned r; asm volatile("v_cvt_pk_bf16_f32 %0, %1, %2" : "=v"(r) : "v"(lo), "v"(hi)); return r; }
; #define LAS __attribute__((address_space(3)))
; __device__ __forceinline__ float bf_lo(unsigned u) { return __uint_as_float(u << 16); }
; __device__ __forceinline__ float bf_hi(unsigned u) { return __uint_as_float(u & 0xffff0000u); }
; __device__ __forceinline__ void pool_phase(LAS unsigned char* lds, const bf16_t* PROJ, const bf16_t* PW, const float* pscale, bf16_t* Y, float* SS, int bx, int G) {
;     ...
;             for (int j = 1; j < 16; ++j) if (j < w) { s0 += bf_lo(xr[15 - j]); s1 += bf_hi(xr[15 - j]); }
; #pragma unroll
;             for (int tt = 0; tt < 16; ++tt) { const int t = t_start + tt; const unsigned x = xr[tt + 15]; const float x0 = bf_lo(x), x1 = bf_hi(x);
;                 s0 += x0; s1 += x1; const int pos = pos0 + t; const float rc = __builtin_amdgcn_rcpf((float)((pos + 1 < w) ? (pos + 1) : w));
;                 const float d0 = s0 * rc - x0, d1 = s1 * rc - x1;
;                 *(LAS unsigned*)(lds + PL_DT + t * PL_DROW + cp * 4) = cvt_pk_bf16(d0, d1);
;                 const unsigned xo = (w == 2) ? xr[tt + 14] : (w == 4) ? xr[tt + 12] : (w == 8) ? xr[tt + 8] : xr[tt]; s0 -= bf_lo(xo); s1 -= bf_hi(xo); }
	v_lshlrev_b32_e32 v147, 16, v150
	v_sub_f32_e32 v153, v153, v146
	v_rcp_iflag_f32_e32 v154, v154
	v_and_b32_e32 v146, 0xffff0000, v150
	v_add_f32_e32 v150, v152, v147
	v_add_f32_e32 v152, v153, v146
	v_fma_f32 v153, v154, v150, -v147
	v_fma_f32 v154, v154, v152, -v146
	v_cvt_pk_bf16_f32 v153, v153, v154
	ds_write_b32 v194, v153 offset:43072
	v_add_u32_e32 v153, s72, v164
	v_min_i32_e32 v153, s78, v153
	v_cvt_f32_i32_e32 v153, v153
	v_sub_f32_e32 v150, v150, v149
	v_lshlrev_b32_e32 v149, 16, v151
	v_sub_f32_e32 v152, v152, v148
	v_rcp_iflag_f32_e32 v153, v153
	v_and_b32_e32 v148, 0xffff0000, v151
	v_add_f32_e32 v150, v150, v149
	v_add_f32_e32 v151, v152, v148
	v_fma_f32 v152, v153, v150, -v149
	v_fma_f32 v153, v153, v151, -v148
	v_cvt_pk_bf16_f32 v152, v152, v153
	ds_write_b32 v194, v152 offset:43600
	v_add_u32_e32 v152, s72, v165
	v_min_i32_e32 v152, s78, v152
	v_cvt_f32_i32_e32 v152, v152
	v_sub_f32_e32 v150, v150, v143
	s_waitcnt lgkmcnt(10)
	v_lshlrev_b32_e32 v143, 16, v126
	v_sub_f32_e32 v151, v151, v142
	v_rcp_iflag_f32_e32 v152, v152
	v_and_b32_e32 v142, 0xffff0000, v126
	v_add_f32_e32 v126, v150, v143
	v_add_f32_e32 v150, v151, v142
	v_fma_f32 v151, v152, v126, -v143
	v_fma_f32 v152, v152, v150, -v142
	v_cvt_pk_bf16_f32 v151, v151, v152
	ds_write_b32 v194, v151 offset:44128
	v_add_u32_e32 v151, s72, v166
	v_min_i32_e32 v151, s78, v151
	v_cvt_f32_i32_e32 v151, v151
	v_sub_f32_e32 v126, v126, v139
	v_lshlrev_b32_e32 v139, 16, v127
	v_sub_f32_e32 v150, v150, v138
	v_rcp_iflag_f32_e32 v151, v151
	v_and_b32_e32 v138, 0xffff0000, v127
	v_add_f32_e32 v126, v126, v139
	v_add_f32_e32 v127, v150, v138
	v_fma_f32 v150, v151, v126, -v139
	v_fma_f32 v151, v151, v127, -v138
	v_cvt_pk_bf16_f32 v150, v150, v151
	ds_write_b32 v194, v150 offset:44656
	v_mov_b64_e32 v[124:125], v[128:129]
	v_add_u32_e32 v128, s72, v167
	v_min_i32_e32 v128, s78, v128
	v_cvt_f32_i32_e32 v128, v128
	v_sub_f32_e32 v126, v126, v125
	s_waitcnt lgkmcnt(11)
	v_lshlrev_b32_e32 v125, 16, v118
	v_sub_f32_e32 v127, v127, v124
	v_rcp_iflag_f32_e32 v128, v128
	v_and_b32_e32 v124, 0xffff0000, v118
	v_add_f32_e32 v118, v126, v125
	v_add_f32_e32 v126, v127, v124
	v_fma_f32 v127, v128, v118, -v125
	v_fma_f32 v128, v128, v126, -v124
	v_cvt_pk_bf16_f32 v127, v127, v128
	ds_write_b32 v194, v127 offset:45184
	v_mov_b64_e32 v[136:137], v[122:123]
	v_add_u32_e32 v122, s72, v168
	v_min_i32_e32 v122, s78, v122
	v_cvt_f32_i32_e32 v122, v122
	v_sub_f32_e32 v118, v118, v137
	v_lshlrev_b32_e32 v123, 16, v119
	v_sub_f32_e32 v126, v126, v136
	v_rcp_iflag_f32_e32 v127, v122
	v_and_b32_e32 v122, 0xffff0000, v119
	v_add_f32_e32 v118, v118, v123
	v_add_f32_e32 v119, v126, v122
	v_fma_f32 v126, v127, v118, -v123
	v_fma_f32 v127, v127, v119, -v122
	v_cvt_pk_bf16_f32 v126, v126, v127
	ds_write_b32 v194, v126 offset:45712
	v_mov_b64_e32 v[140:141], v[120:121]
	v_add_u32_e32 v120, s72, v169
	v_min_i32_e32 v120, s78, v120
	v_cvt_f32_i32_e32 v120, v120
	v_sub_f32_e32 v121, v118, v141
	v_sub_f32_e32 v126, v119, v140
	s_waitcnt lgkmcnt(12)
	v_lshlrev_b32_e32 v119, 16, v114
	v_rcp_iflag_f32_e32 v127, v120
	v_and_b32_e32 v118, 0xffff0000, v114
	v_add_f32_e32 v114, v121, v119
	v_add_f32_e32 v120, v126, v118
	v_fma_f32 v121, v127, v114, -v119
	v_fma_f32 v126, v127, v120, -v118
	v_cvt_pk_bf16_f32 v121, v121, v126
	ds_write_b32 v194, v121 offset:46240
	v_mov_b64_e32 v[144:145], v[116:117]
	v_add_u32_e32 v116, s72, v170
	v_min_i32_e32 v116, s78, v116
	v_cvt_f32_i32_e32 v116, v116
	v_sub_f32_e32 v114, v114, v145
	v_lshlrev_b32_e32 v117, 16, v115
	v_sub_f32_e32 v120, v120, v144
	v_rcp_iflag_f32_e32 v121, v116
	v_and_b32_e32 v116, 0xffff0000, v115
	v_add_f32_e32 v114, v114, v117
	v_add_f32_e32 v115, v120, v116
	v_fma_f32 v120, v121, v114, -v117
	v_fma_f32 v121, v121, v115, -v116
	v_cvt_pk_bf16_f32 v120, v120, v121
	ds_write_b32 v194, v120 offset:46768
	v_mov_b64_e32 v[146:147], v[112:113]
	v_add_u32_e32 v112, s72, v171
	v_min_i32_e32 v112, s78, v112
	v_cvt_f32_i32_e32 v112, v112
	v_sub_f32_e32 v114, v114, v147
	s_waitcnt lgkmcnt(13)
	v_lshlrev_b32_e32 v113, 16, v108
	v_sub_f32_e32 v115, v115, v146
	v_rcp_iflag_f32_e32 v120, v112
	v_and_b32_e32 v112, 0xffff0000, v108
	v_add_f32_e32 v108, v114, v113
	v_add_f32_e32 v114, v115, v112
	v_fma_f32 v115, v120, v108, -v113
	v_fma_f32 v120, v120, v114, -v112
	v_cvt_pk_bf16_f32 v115, v115, v120
	ds_write_b32 v194, v115 offset:47296
	v_mov_b64_e32 v[148:149], v[110:111]
	v_add_u32_e32 v110, s72, v172
	v_min_i32_e32 v110, s78, v110
	v_cvt_f32_i32_e32 v110, v110
	v_sub_f32_e32 v108, v108, v149
	v_lshlrev_b32_e32 v111, 16, v109
	v_sub_f32_e32 v114, v114, v148
	v_rcp_iflag_f32_e32 v115, v110
	v_and_b32_e32 v110, 0xffff0000, v109
	v_add_f32_e32 v108, v108, v111
	v_add_f32_e32 v109, v114, v110
	v_fma_f32 v114, v115, v108, -v111
	v_fma_f32 v115, v115, v109, -v110
	v_cvt_pk_bf16_f32 v114, v114, v115
	ds_write_b32 v194, v114 offset:47824
	v_mov_b64_e32 v[142:143], v[106:107]
	v_add_u32_e32 v106, s72, v173
	v_min_i32_e32 v106, s78, v106
	v_cvt_f32_i32_e32 v106, v106
	v_sub_f32_e32 v107, v108, v143
	v_sub_f32_e32 v108, v109, v142
	s_waitcnt lgkmcnt(14)
	v_lshlrev_b32_e32 v109, 16, v102
	v_rcp_iflag_f32_e32 v112, v106
	v_and_b32_e32 v113, 0xffff0000, v102
	v_add_f32_e32 v102, v107, v109
	v_add_f32_e32 v106, v108, v113
	v_fma_f32 v107, v112, v102, -v109
	v_fma_f32 v108, v112, v106, -v113
	v_cvt_pk_bf16_f32 v107, v107, v108
	ds_write_b32 v194, v107 offset:48352
	v_mov_b64_e32 v[138:139], v[104:105]
	v_add_u32_e32 v104, s72, v174
	v_min_i32_e32 v104, s78, v104
	v_cvt_f32_i32_e32 v104, v104
	v_sub_f32_e32 v102, v102, v139
	v_sub_f32_e32 v105, v106, v138
	v_lshlrev_b32_e32 v106, 16, v103
	v_rcp_iflag_f32_e32 v104, v104
	v_and_b32_e32 v103, 0xffff0000, v103
	v_add_f32_e32 v102, v102, v106
	v_add_f32_e32 v105, v105, v103
	v_fma_f32 v102, v104, v102, -v106
	v_fma_f32 v103, v104, v105, -v103
	v_cvt_pk_bf16_f32 v102, v102, v103
	ds_write_b32 v190, v102 offset:40960
	s_waitcnt lgkmcnt(0)
	s_branch .Lpool_sw_join
; __device__ __forceinline__ unsigned cvt_pk_bf16(float lo, float hi) { unsigned r; asm volatile("v_cvt_pk_bf16_f32 %0, %1, %2" : "=v"(r) : "v"(lo), "v"(hi)); return r; }
; #define LAS __attribute__((address_space(3)))
; __device__ __forceinline__ float bf_lo(unsigned u) { return __uint_as_float(u << 16); }
; __device__ __forceinline__ float bf_hi(unsigned u) { return __uint_as_float(u & 0xffff0000u); }
; __device__ __forceinline__ void pool_phase(LAS unsigned char* lds, const bf16_t* PROJ, const bf16_t* PW, const float* pscale, bf16_t* Y, float* SS, int bx, int G) {
;     ...
;             unsigned xr[31];
; #pragma unroll
;             for (int r = 0; r < 31; ++r) xr[r] = xs[(t_start + r + 1) * 128];
;             float s0 = 0.f, s1 = 0.f;
; #pragma unroll
;             for (int j = 1; j < 16; ++j) if (j < w) { s0 += bf_lo(xr[15 - j]); s1 += bf_hi(xr[15 - j]); }
; #pragma unroll
;             for (int tt = 0; tt < 16; ++tt) { const int t = t_start + tt; const unsigned x = xr[tt + 15]; const float x0 = bf_lo(x), x1 = bf_hi(x);
;                 s0 += x0; s1 += x1; const int pos = pos0 + t; const float rc = __builtin_amdgcn_rcpf((float)((pos + 1 < w) ? (pos + 1) : w));
;                 const float d0 = s0 * rc - x0, d1 = s1 * rc - x1;
;                 *(LAS unsigned*)(lds + PL_DT + t * PL_DROW + cp * 4) = cvt_pk_bf16(d0, d1);
;                 const unsigned xo = (w == 2) ? xr[tt + 14] : (w == 4) ? xr[tt + 12] : (w == 8) ? xr[tt + 8] : xr[tt]; s0 -= bf_lo(xo); s1 -= bf_hi(xo); }
.Lpool_g0:
	ds_read2st64_b32 v[124:125], v188 offset0:2 offset1:4
	ds_read2st64_b32 v[136:137], v188 offset0:6 offset1:8
	ds_read2st64_b32 v[140:141], v188 offset0:10 offset1:12
	ds_read2st64_b32 v[138:139], v188 offset0:14 offset1:16
	ds_read2st64_b32 v[122:123], v188 offset0:18 offset1:20
	ds_read2st64_b32 v[116:117], v188 offset0:22 offset1:24
	ds_read2st64_b32 v[110:111], v188 offset0:26 offset1:28
	ds_read2st64_b32 v[154:155], v188 offset0:30 offset1:34
	ds_read_b32 v181, v189 offset:512
	ds_read2st64_b32 v[152:153], v188 offset0:36 offset1:38
	ds_read2st64_b32 v[150:151], v188 offset0:40 offset1:42
	ds_read2st64_b32 v[126:127], v188 offset0:44 offset1:46
	ds_read2st64_b32 v[118:119], v188 offset0:48 offset1:50
	ds_read2st64_b32 v[114:115], v188 offset0:52 offset1:54
	ds_read2st64_b32 v[108:109], v188 offset0:56 offset1:58
	ds_read2st64_b32 v[102:103], v188 offset0:60 offset1:62
	s_waitcnt lgkmcnt(8)
	v_lshlrev_b32_e32 v105, 16, v154
	v_and_b32_e32 v104, 0xffff0000, v154
	v_add_f32_e32 v112, 0, v105
	v_add_f32_e32 v113, 0, v104
	v_lshlrev_b32_e32 v107, 16, v111
	v_and_b32_e32 v106, 0xffff0000, v111
	v_add_f32_e32 v120, v112, v107
	v_add_f32_e32 v121, v113, v106
	v_lshlrev_b32_e32 v111, 16, v110
	v_and_b32_e32 v110, 0xffff0000, v110
	s_add_i32 s88, s76, s79
	v_add_f32_e32 v120, v120, v111
	v_add_f32_e32 v121, v121, v110
	s_ashr_i32 s70, s88, 31
	v_cndmask_b32_e64 v128, v121, v113, s[10:11]
	v_cndmask_b32_e64 v129, v120, v112, s[10:11]
	v_lshlrev_b32_e32 v113, 16, v117
	v_and_b32_e32 v112, 0xffff0000, v117
	s_lshr_b32 s70, s70, 20
	v_add_f32_e32 v120, v129, v113
	v_add_f32_e32 v121, v128, v112
	v_lshlrev_b32_e32 v117, 16, v116
	v_and_b32_e32 v116, 0xffff0000, v116
	s_add_i32 s70, s88, s70
	v_add_f32_e32 v142, v120, v117
	v_add_f32_e32 v143, v121, v116
	v_lshlrev_b32_e32 v121, 16, v123
	v_and_b32_e32 v120, 0xffff0000, v123
	s_and_b32 s70, s70, 0xfffff000
	v_add_f32_e32 v142, v142, v121
	v_add_f32_e32 v143, v143, v120
	v_lshlrev_b32_e32 v123, 16, v122
	v_and_b32_e32 v122, 0xffff0000, v122
	s_sub_i32 s70, s88, s70
	v_add_f32_e32 v142, v142, v123
	v_add_f32_e32 v143, v143, v122
	v_cndmask_b32_e64 v154, v128, v143, s[12:13]
	v_cndmask_b32_e64 v195, v129, v142, s[12:13]
	v_lshlrev_b32_e32 v129, 16, v139
	v_and_b32_e32 v128, 0xffff0000, v139
	s_or_b32 s72, s70, 1
	v_lshlrev_b32_e32 v139, 16, v138
	v_and_b32_e32 v138, 0xffff0000, v138
	v_lshlrev_b32_e32 v143, 16, v141
	v_and_b32_e32 v142, 0xffff0000, v141
	v_lshlrev_b32_e32 v149, 16, v140
	v_and_b32_e32 v148, 0xffff0000, v140
	v_lshlrev_b32_e32 v147, 16, v137
	v_and_b32_e32 v146, 0xffff0000, v137
	v_lshlrev_b32_e32 v145, 16, v136
	v_and_b32_e32 v144, 0xffff0000, v136
	v_lshlrev_b32_e32 v141, 16, v125
	v_and_b32_e32 v140, 0xffff0000, v125
	v_lshlrev_b32_e32 v137, 16, v124
	v_and_b32_e32 v136, 0xffff0000, v124
	s_waitcnt lgkmcnt(7)
	v_lshlrev_b32_e32 v125, 16, v181
	v_and_b32_e32 v124, 0xffff0000, v181
	v_add_f32_e32 v181, v195, v129
	v_add_f32_e32 v196, v154, v128
	v_add_u32_e32 v197, s72, v1
	v_add_f32_e32 v181, v181, v139
	v_add_f32_e32 v196, v196, v138
	v_min_i32_e32 v197, s78, v197
	v_add_f32_e32 v181, v181, v143
	v_add_f32_e32 v196, v196, v142
	v_cvt_f32_i32_e32 v197, v197
	v_add_f32_e32 v181, v181, v149
	v_add_f32_e32 v196, v196, v148
	v_add_f32_e32 v181, v181, v147
	v_add_f32_e32 v196, v196, v146
	v_add_f32_e32 v181, v181, v145
	v_add_f32_e32 v196, v196, v144
	v_add_f32_e32 v181, v181, v141
	v_add_f32_e32 v196, v196, v140
	v_rcp_iflag_f32_e32 v197, v197
	v_add_f32_e32 v181, v181, v137
	v_add_f32_e32 v196, v196, v136
	v_cndmask_b32_e64 v196, v154, v196, s[14:15]
	v_cndmask_b32_e64 v154, v195, v181, s[14:15]
	v_add_f32_e32 v154, v154, v125
	v_add_f32_e32 v195, v196, v124
	v_fma_f32 v181, v197, v154, -v125
	v_fma_f32 v196, v197, v195, -v124
	v_cvt_pk_bf16_f32 v181, v181, v196
	ds_write_b32 v194, v181 offset:40960
	v_mov_b64_e32 v[136:137], v[104:105]
	v_add_u32_e32 v181, s72, v160
	v_min_i32_e32 v181, s78, v181
	v_cvt_f32_i32_e32 v181, v181
	v_sub_f32_e32 v154, v154, v137
	v_sub_f32_e32 v195, v195, v136
	v_lshlrev_b32_e32 v137, 16, v155
	v_rcp_iflag_f32_e32 v181, v181
	v_and_b32_e32 v136, 0xffff0000, v155
	v_add_f32_e32 v154, v154, v137
	v_add_f32_e32 v155, v195, v136
	v_fma_f32 v195, v181, v154, -v137
	v_fma_f32 v181, v181, v155, -v136
	v_cvt_pk_bf16_f32 v181, v195, v181
	ds_write_b32 v194, v181 offset:41488
	v_mov_b64_e32 v[140:141], v[124:125]
	v_add_u32_e32 v181, s72, v161
	v_min_i32_e32 v181, s78, v181
	v_cvt_f32_i32_e32 v181, v181
	v_sub_f32_e32 v154, v154, v141
	s_waitcnt lgkmcnt(8)
	v_lshlrev_b32_e32 v141, 16, v152
	v_sub_f32_e32 v155, v155, v140
	v_rcp_iflag_f32_e32 v181, v181
	v_and_b32_e32 v140, 0xffff0000, v152
	v_add_f32_e32 v152, v154, v141
	v_add_f32_e32 v154, v155, v140
	v_fma_f32 v155, v181, v152, -v141
	v_fma_f32 v181, v181, v154, -v140
	v_cvt_pk_bf16_f32 v155, v155, v181
	ds_write_b32 v194, v155 offset:42016
	v_mov_b64_e32 v[144:145], v[136:137]
	v_add_u32_e32 v155, s72, v162
	v_min_i32_e32 v155, s78, v155
	v_cvt_f32_i32_e32 v155, v155
	v_sub_f32_e32 v152, v152, v145
	v_lshlrev_b32_e32 v145, 16, v153
	v_sub_f32_e32 v154, v154, v144
	v_rcp_iflag_f32_e32 v155, v155
	v_and_b32_e32 v144, 0xffff0000, v153
	v_add_f32_e32 v152, v152, v145
	v_add_f32_e32 v153, v154, v144
	v_fma_f32 v154, v155, v152, -v145
	v_fma_f32 v155, v155, v153, -v144
	v_cvt_pk_bf16_f32 v154, v154, v155
	ds_write_b32 v194, v154 offset:42544
	v_mov_b64_e32 v[146:147], v[140:141]
	v_add_u32_e32 v154, s72, v163
	v_min_i32_e32 v154, s78, v154
	v_cvt_f32_i32_e32 v154, v154
	v_sub_f32_e32 v152, v152, v147
	s_waitcnt lgkmcnt(9)
; __device__ __forceinline__ unsigned cvt_pk_bf16(float lo, float hi) { unsigned r; asm volatile("v_cvt_pk_bf16_f32 %0, %1, %2" : "=v"(r) : "v"(lo), "v"(hi)); return r; }
; #define LAS __attribute__((address_space(3)))
; __device__ __forceinline__ float bf_lo(unsigned u) { return __uint_as_float(u << 16); }
; __device__ __forceinline__ float bf_hi(unsigned u) { return __uint_as_float(u & 0xffff0000u); }
; __device__ __forceinline__ void pool_phase(LAS unsigned char* lds, const bf16_t* PROJ, const bf16_t* PW, const float* pscale, bf16_t* Y, float* SS, int bx, int G) {
;     ...
;             for (int j = 1; j < 16; ++j) if (j < w) { s0 += bf_lo(xr[15 - j]); s1 += bf_hi(xr[15 - j]); }
; #pragma unroll
;             for (int tt = 0; tt < 16; ++tt) { const int t = t_start + tt; const unsigned x = xr[tt + 15]; const float x0 = bf_lo(x), x1 = bf_hi(x);
;                 s0 += x0; s1 += x1; const int pos = pos0 + t; const float rc = __builtin_amdgcn_rcpf((float)((pos + 1 < w) ? (pos + 1) : w));
;                 const float d0 = s0 * rc - x0, d1 = s1 * rc - x1;
;                 *(LAS unsigned*)(lds + PL_DT + t * PL_DROW + cp * 4) = cvt_pk_bf16(d0, d1);
;                 const unsigned xo = (w == 2) ? xr[tt + 14] : (w == 4) ? xr[tt + 12] : (w == 8) ? xr[tt + 8] : xr[tt]; s0 -= bf_lo(xo); s1 -= bf_hi(xo); }
	v_lshlrev_b32_e32 v147, 16, v150
	v_sub_f32_e32 v153, v153, v146
	v_rcp_iflag_f32_e32 v154, v154
	v_and_b32_e32 v146, 0xffff0000, v150
	v_add_f32_e32 v150, v152, v147
	v_add_f32_e32 v152, v153, v146
	v_fma_f32 v153, v154, v150, -v147
	v_fma_f32 v154, v154, v152, -v146
	v_cvt_pk_bf16_f32 v153, v153, v154
	ds_write_b32 v194, v153 offset:43072
	v_mov_b64_e32 v[148:149], v[144:145]
	v_add_u32_e32 v153, s72, v164
	v_min_i32_e32 v153, s78, v153
	v_cvt_f32_i32_e32 v153, v153
	v_sub_f32_e32 v150, v150, v149
	v_lshlrev_b32_e32 v149, 16, v151
	v_sub_f32_e32 v152, v152, v148
	v_rcp_iflag_f32_e32 v153, v153
	v_and_b32_e32 v148, 0xffff0000, v151
	v_add_f32_e32 v150, v150, v149
	v_add_f32_e32 v151, v152, v148
	v_fma_f32 v152, v153, v150, -v149
	v_fma_f32 v153, v153, v151, -v148
	v_cvt_pk_bf16_f32 v152, v152, v153
	ds_write_b32 v194, v152 offset:43600
	v_mov_b64_e32 v[142:143], v[146:147]
	v_add_u32_e32 v152, s72, v165
	v_min_i32_e32 v152, s78, v152
	v_cvt_f32_i32_e32 v152, v152
	v_sub_f32_e32 v150, v150, v143
	s_waitcnt lgkmcnt(10)
	v_lshlrev_b32_e32 v143, 16, v126
	v_sub_f32_e32 v151, v151, v142
	v_rcp_iflag_f32_e32 v152, v152
	v_and_b32_e32 v142, 0xffff0000, v126
	v_add_f32_e32 v126, v150, v143
	v_add_f32_e32 v150, v151, v142
	v_fma_f32 v151, v152, v126, -v143
	v_fma_f32 v152, v152, v150, -v142
	v_cvt_pk_bf16_f32 v151, v151, v152
	ds_write_b32 v194, v151 offset:44128
	v_mov_b64_e32 v[138:139], v[148:149]
	v_add_u32_e32 v151, s72, v166
	v_min_i32_e32 v151, s78, v151
	v_cvt_f32_i32_e32 v151, v151
	v_sub_f32_e32 v126, v126, v139
	v_lshlrev_b32_e32 v139, 16, v127
	v_sub_f32_e32 v150, v150, v138
	v_rcp_iflag_f32_e32 v151, v151
	v_and_b32_e32 v138, 0xffff0000, v127
	v_add_f32_e32 v126, v126, v139
	v_add_f32_e32 v127, v150, v138
	v_fma_f32 v150, v151, v126, -v139
	v_fma_f32 v151, v151, v127, -v138
	v_cvt_pk_bf16_f32 v150, v150, v151
	ds_write_b32 v194, v150 offset:44656
	v_mov_b64_e32 v[124:125], v[142:143]
	v_add_u32_e32 v128, s72, v167
	v_min_i32_e32 v128, s78, v128
	v_cvt_f32_i32_e32 v128, v128
	v_sub_f32_e32 v126, v126, v125
	s_waitcnt lgkmcnt(11)
	v_lshlrev_b32_e32 v125, 16, v118
	v_sub_f32_e32 v127, v127, v124
	v_rcp_iflag_f32_e32 v128, v128
	v_and_b32_e32 v124, 0xffff0000, v118
	v_add_f32_e32 v118, v126, v125
	v_add_f32_e32 v126, v127, v124
	v_fma_f32 v127, v128, v118, -v125
	v_fma_f32 v128, v128, v126, -v124
	v_cvt_pk_bf16_f32 v127, v127, v128
	ds_write_b32 v194, v127 offset:45184
	v_mov_b64_e32 v[136:137], v[138:139]
	v_add_u32_e32 v122, s72, v168
	v_min_i32_e32 v122, s78, v122
	v_cvt_f32_i32_e32 v122, v122
	v_sub_f32_e32 v118, v118, v137
	v_lshlrev_b32_e32 v123, 16, v119
	v_sub_f32_e32 v126, v126, v136
	v_rcp_iflag_f32_e32 v127, v122
	v_and_b32_e32 v122, 0xffff0000, v119
	v_add_f32_e32 v118, v118, v123
	v_add_f32_e32 v119, v126, v122
	v_fma_f32 v126, v127, v118, -v123
	v_fma_f32 v127, v127, v119, -v122
	v_cvt_pk_bf16_f32 v126, v126, v127
	ds_write_b32 v194, v126 offset:45712
	v_mov_b64_e32 v[140:141], v[124:125]
	v_add_u32_e32 v120, s72, v169
	v_min_i32_e32 v120, s78, v120
	v_cvt_f32_i32_e32 v120, v120
	v_sub_f32_e32 v121, v118, v141
	v_sub_f32_e32 v126, v119, v140
	s_waitcnt lgkmcnt(12)
	v_lshlrev_b32_e32 v119, 16, v114
	v_rcp_iflag_f32_e32 v127, v120
	v_and_b32_e32 v118, 0xffff0000, v114
	v_add_f32_e32 v114, v121, v119
	v_add_f32_e32 v120, v126, v118
	v_fma_f32 v121, v127, v114, -v119
	v_fma_f32 v126, v127, v120, -v118
	v_cvt_pk_bf16_f32 v121, v121, v126
	ds_write_b32 v194, v121 offset:46240
	v_mov_b64_e32 v[144:145], v[122:123]
	v_add_u32_e32 v116, s72, v170
	v_min_i32_e32 v116, s78, v116
	v_cvt_f32_i32_e32 v116, v116
	v_sub_f32_e32 v114, v114, v145
	v_lshlrev_b32_e32 v117, 16, v115
	v_sub_f32_e32 v120, v120, v144
	v_rcp_iflag_f32_e32 v121, v116
	v_and_b32_e32 v116, 0xffff0000, v115
	v_add_f32_e32 v114, v114, v117
	v_add_f32_e32 v115, v120, v116
	v_fma_f32 v120, v121, v114, -v117
	v_fma_f32 v121, v121, v115, -v116
	v_cvt_pk_bf16_f32 v120, v120, v121
	ds_write_b32 v194, v120 offset:46768
	v_mov_b64_e32 v[146:147], v[118:119]
	v_add_u32_e32 v112, s72, v171
	v_min_i32_e32 v112, s78, v112
	v_cvt_f32_i32_e32 v112, v112
	v_sub_f32_e32 v114, v114, v147
	s_waitcnt lgkmcnt(13)
	v_lshlrev_b32_e32 v113, 16, v108
	v_sub_f32_e32 v115, v115, v146
	v_rcp_iflag_f32_e32 v120, v112
	v_and_b32_e32 v112, 0xffff0000, v108
	v_add_f32_e32 v108, v114, v113
	v_add_f32_e32 v114, v115, v112
	v_fma_f32 v115, v120, v108, -v113
	v_fma_f32 v120, v120, v114, -v112
	v_cvt_pk_bf16_f32 v115, v115, v120
	ds_write_b32 v194, v115 offset:47296
	v_mov_b64_e32 v[148:149], v[116:117]
	v_add_u32_e32 v110, s72, v172
	v_min_i32_e32 v110, s78, v110
	v_cvt_f32_i32_e32 v110, v110
	v_sub_f32_e32 v108, v108, v149
	v_lshlrev_b32_e32 v111, 16, v109
	v_sub_f32_e32 v114, v114, v148
	v_rcp_iflag_f32_e32 v115, v110
	v_and_b32_e32 v110, 0xffff0000, v109
	v_add_f32_e32 v108, v108, v111
	v_add_f32_e32 v109, v114, v110
	v_fma_f32 v114, v115, v108, -v111
	v_fma_f32 v115, v115, v109, -v110
	v_cvt_pk_bf16_f32 v114, v114, v115
	ds_write_b32 v194, v114 offset:47824
	v_mov_b64_e32 v[142:143], v[112:113]
	v_add_u32_e32 v106, s72, v173
	v_min_i32_e32 v106, s78, v106
	v_cvt_f32_i32_e32 v106, v106
	v_sub_f32_e32 v107, v108, v143
	v_sub_f32_e32 v108, v109, v142
	s_waitcnt lgkmcnt(14)
	v_lshlrev_b32_e32 v109, 16, v102
	v_rcp_iflag_f32_e32 v112, v106
	v_and_b32_e32 v113, 0xffff0000, v102
	v_add_f32_e32 v102, v107, v109
	v_add_f32_e32 v106, v108, v113
	v_fma_f32 v107, v112, v102, -v109
	v_fma_f32 v108, v112, v106, -v113
	v_cvt_pk_bf16_f32 v107, v107, v108
	ds_write_b32 v194, v107 offset:48352
	v_mov_b64_e32 v[138:139], v[110:111]
	v_add_u32_e32 v104, s72, v174
	v_min_i32_e32 v104, s78, v104
	v_cvt_f32_i32_e32 v104, v104
	v_sub_f32_e32 v102, v102, v139
	v_sub_f32_e32 v105, v106, v138
	v_lshlrev_b32_e32 v106, 16, v103
	v_rcp_iflag_f32_e32 v104, v104
	v_and_b32_e32 v103, 0xffff0000, v103
	v_add_f32_e32 v102, v102, v106
	v_add_f32_e32 v105, v105, v103
	v_fma_f32 v102, v104, v102, -v106
	v_fma_f32 v103, v104, v105, -v103
	v_cvt_pk_bf16_f32 v102, v102, v103
	ds_write_b32 v190, v102 offset:40960
	s_waitcnt lgkmcnt(0)
	s_branch .Lpool_sw_join
; __device__ __forceinline__ unsigned cvt_pk_bf16(float lo, float hi) { unsigned r; asm volatile("v_cvt_pk_bf16_f32 %0, %1, %2" : "=v"(r) : "v"(lo), "v"(hi)); return r; }
; #define LAS __attribute__((address_space(3)))
; __device__ __forceinline__ float bf_lo(unsigned u) { return __uint_as_float(u << 16); }
; __device__ __forceinline__ float bf_hi(unsigned u) { return __uint_as_float(u & 0xffff0000u); }
; __device__ __forceinline__ void pool_phase(LAS unsigned char* lds, const bf16_t* PROJ, const bf16_t* PW, const float* pscale, bf16_t* Y, float* SS, int bx, int G) {
;     ...
;             unsigned xr[31];
; #pragma unroll
;             for (int r = 0; r < 31; ++r) xr[r] = xs[(t_start + r + 1) * 128];
;             float s0 = 0.f, s1 = 0.f;
; #pragma unroll
;             for (int j = 1; j < 16; ++j) if (j < w) { s0 += bf_lo(xr[15 - j]); s1 += bf_hi(xr[15 - j]); }
; #pragma unroll
;             for (int tt = 0; tt < 16; ++tt) { const int t = t_start + tt; const unsigned x = xr[tt + 15]; const float x0 = bf_lo(x), x1 = bf_hi(x);
;                 s0 += x0; s1 += x1; const int pos = pos0 + t; const float rc = __builtin_amdgcn_rcpf((float)((pos + 1 < w) ? (pos + 1) : w));
;                 const float d0 = s0 * rc - x0, d1 = s1 * rc - x1;
;                 *(LAS unsigned*)(lds + PL_DT + t * PL_DROW + cp * 4) = cvt_pk_bf16(d0, d1);
;                 const unsigned xo = (w == 2) ? xr[tt + 14] : (w == 4) ? xr[tt + 12] : (w == 8) ? xr[tt + 8] : xr[tt]; s0 -= bf_lo(xo); s1 -= bf_hi(xo); }
.Lpool_g1:
	ds_read2st64_b32 v[124:125], v188 offset0:2 offset1:4
	ds_read2st64_b32 v[136:137], v188 offset0:6 offset1:8
	ds_read2st64_b32 v[140:141], v188 offset0:10 offset1:12
	ds_read2st64_b32 v[138:139], v188 offset0:14 offset1:16
	ds_read2st64_b32 v[122:123], v188 offset0:18 offset1:20
	ds_read2st64_b32 v[116:117], v188 offset0:22 offset1:24
	ds_read2st64_b32 v[110:111], v188 offset0:26 offset1:28
	ds_read2st64_b32 v[154:155], v188 offset0:30 offset1:34
	ds_read_b32 v181, v189 offset:512
	ds_read2st64_b32 v[152:153], v188 offset0:36 offset1:38
	ds_read2st64_b32 v[150:151], v188 offset0:40 offset1:42
	ds_read2st64_b32 v[126:127], v188 offset0:44 offset1:46
	ds_read2st64_b32 v[118:119], v188 offset0:48 offset1:50
	ds_read2st64_b32 v[114:115], v188 offset0:52 offset1:54
	ds_read2st64_b32 v[108:109], v188 offset0:56 offset1:58
	ds_read2st64_b32 v[102:103], v188 offset0:60 offset1:62
	s_waitcnt lgkmcnt(8)
	v_lshlrev_b32_e32 v105, 16, v154
	v_and_b32_e32 v104, 0xffff0000, v154
	v_add_f32_e32 v112, 0, v105
	v_add_f32_e32 v113, 0, v104
	v_lshlrev_b32_e32 v107, 16, v111
	v_and_b32_e32 v106, 0xffff0000, v111
	v_add_f32_e32 v120, v112, v107
	v_add_f32_e32 v121, v113, v106
	v_lshlrev_b32_e32 v111, 16, v110
	v_and_b32_e32 v110, 0xffff0000, v110
	s_add_i32 s88, s76, s79
	v_add_f32_e32 v120, v120, v111
	v_add_f32_e32 v121, v121, v110
	s_ashr_i32 s70, s88, 31
	v_cndmask_b32_e64 v128, v121, v113, s[10:11]
	v_cndmask_b32_e64 v129, v120, v112, s[10:11]
	v_lshlrev_b32_e32 v113, 16, v117
	v_and_b32_e32 v112, 0xffff0000, v117
	s_lshr_b32 s70, s70, 20
	v_add_f32_e32 v120, v129, v113
	v_add_f32_e32 v121, v128, v112
	v_lshlrev_b32_e32 v117, 16, v116
	v_and_b32_e32 v116, 0xffff0000, v116
	s_add_i32 s70, s88, s70
	v_add_f32_e32 v142, v120, v117
	v_add_f32_e32 v143, v121, v116
	v_lshlrev_b32_e32 v121, 16, v123
	v_and_b32_e32 v120, 0xffff0000, v123
	s_and_b32 s70, s70, 0xfffff000
	v_add_f32_e32 v142, v142, v121
	v_add_f32_e32 v143, v143, v120
	v_lshlrev_b32_e32 v123, 16, v122
	v_and_b32_e32 v122, 0xffff0000, v122
	s_sub_i32 s70, s88, s70
	v_add_f32_e32 v142, v142, v123
	v_add_f32_e32 v143, v143, v122
	v_cndmask_b32_e64 v154, v128, v143, s[12:13]
	v_cndmask_b32_e64 v195, v129, v142, s[12:13]
	v_lshlrev_b32_e32 v129, 16, v139
	v_and_b32_e32 v128, 0xffff0000, v139
	s_or_b32 s72, s70, 1
	v_lshlrev_b32_e32 v139, 16, v138
	v_and_b32_e32 v138, 0xffff0000, v138
	v_lshlrev_b32_e32 v143, 16, v141
	v_and_b32_e32 v142, 0xffff0000, v141
	v_lshlrev_b32_e32 v149, 16, v140
	v_and_b32_e32 v148, 0xffff0000, v140
	v_lshlrev_b32_e32 v147, 16, v137
	v_and_b32_e32 v146, 0xffff0000, v137
	v_lshlrev_b32_e32 v145, 16, v136
	v_and_b32_e32 v144, 0xffff0000, v136
	v_lshlrev_b32_e32 v141, 16, v125
	v_and_b32_e32 v140, 0xffff0000, v125
	v_lshlrev_b32_e32 v137, 16, v124
	v_and_b32_e32 v136, 0xffff0000, v124
	s_waitcnt lgkmcnt(7)
	v_lshlrev_b32_e32 v125, 16, v181
	v_and_b32_e32 v124, 0xffff0000, v181
	v_add_f32_e32 v181, v195, v129
	v_add_f32_e32 v196, v154, v128
	v_add_u32_e32 v197, s72, v1
	v_add_f32_e32 v181, v181, v139
	v_add_f32_e32 v196, v196, v138
	v_min_i32_e32 v197, s78, v197
	v_add_f32_e32 v181, v181, v143
	v_add_f32_e32 v196, v196, v142
	v_cvt_f32_i32_e32 v197, v197
	v_add_f32_e32 v181, v181, v149
	v_add_f32_e32 v196, v196, v148
	v_add_f32_e32 v181, v181, v147
	v_add_f32_e32 v196, v196, v146
	v_add_f32_e32 v181, v181, v145
	v_add_f32_e32 v196, v196, v144
	v_add_f32_e32 v181, v181, v141
	v_add_f32_e32 v196, v196, v140
	v_rcp_iflag_f32_e32 v197, v197
	v_add_f32_e32 v181, v181, v137
	v_add_f32_e32 v196, v196, v136
	v_cndmask_b32_e64 v196, v154, v196, s[14:15]
	v_cndmask_b32_e64 v154, v195, v181, s[14:15]
	v_add_f32_e32 v154, v154, v125
	v_add_f32_e32 v195, v196, v124
	v_fma_f32 v181, v197, v154, -v125
	v_fma_f32 v196, v197, v195, -v124
	v_cvt_pk_bf16_f32 v181, v181, v196
	ds_write_b32 v194, v181 offset:40960
	v_mov_b64_e32 v[136:137], v[104:105]
	v_mov_b64_e32 v[136:137], v[110:111]
	v_add_u32_e32 v181, s72, v160
	v_min_i32_e32 v181, s78, v181
	v_cvt_f32_i32_e32 v181, v181
	v_sub_f32_e32 v154, v154, v137
	v_sub_f32_e32 v195, v195, v136
	v_lshlrev_b32_e32 v137, 16, v155
	v_rcp_iflag_f32_e32 v181, v181
	v_and_b32_e32 v136, 0xffff0000, v155
	v_add_f32_e32 v154, v154, v137
	v_add_f32_e32 v155, v195, v136
	v_fma_f32 v195, v181, v154, -v137
	v_fma_f32 v181, v181, v155, -v136
	v_cvt_pk_bf16_f32 v181, v195, v181
	ds_write_b32 v194, v181 offset:41488
	v_mov_b64_e32 v[140:141], v[124:125]
	v_mov_b64_e32 v[140:141], v[106:107]
	v_add_u32_e32 v181, s72, v161
	v_min_i32_e32 v181, s78, v181
	v_cvt_f32_i32_e32 v181, v181
	v_sub_f32_e32 v154, v154, v141
	s_waitcnt lgkmcnt(8)
	v_lshlrev_b32_e32 v141, 16, v152
	v_sub_f32_e32 v155, v155, v140
	v_rcp_iflag_f32_e32 v181, v181
	v_and_b32_e32 v140, 0xffff0000, v152
	v_add_f32_e32 v152, v154, v141
	v_add_f32_e32 v154, v155, v140
	v_fma_f32 v155, v181, v152, -v141
	v_fma_f32 v181, v181, v154, -v140
	v_cvt_pk_bf16_f32 v155, v155, v181
	ds_write_b32 v194, v155 offset:42016
	v_mov_b64_e32 v[144:145], v[136:137]
	v_mov_b64_e32 v[144:145], v[104:105]
	v_add_u32_e32 v155, s72, v162
	v_min_i32_e32 v155, s78, v155
	v_cvt_f32_i32_e32 v155, v155
	v_sub_f32_e32 v152, v152, v145
	v_lshlrev_b32_e32 v145, 16, v153
	v_sub_f32_e32 v154, v154, v144
	v_rcp_iflag_f32_e32 v155, v155
	v_and_b32_e32 v144, 0xffff0000, v153
	v_add_f32_e32 v152, v152, v145
	v_add_f32_e32 v153, v154, v144
	v_fma_f32 v154, v155, v152, -v145
	v_fma_f32 v155, v155, v153, -v144
	v_cvt_pk_bf16_f32 v154, v154, v155
	ds_write_b32 v194, v154 offset:42544
	v_mov_b64_e32 v[146:147], v[140:141]
	v_mov_b64_e32 v[146:147], v[124:125]
	v_add_u32_e32 v154, s72, v163
	v_min_i32_e32 v154, s78, v154
	v_cvt_f32_i32_e32 v154, v154
	v_sub_f32_e32 v152, v152, v147
	s_waitcnt lgkmcnt(9)
; __device__ __forceinline__ unsigned cvt_pk_bf16(float lo, float hi) { unsigned r; asm volatile("v_cvt_pk_bf16_f32 %0, %1, %2" : "=v"(r) : "v"(lo), "v"(hi)); return r; }
; #define LAS __attribute__((address_space(3)))
; __device__ __forceinline__ float bf_lo(unsigned u) { return __uint_as_float(u << 16); }
; __device__ __forceinline__ float bf_hi(unsigned u) { return __uint_as_float(u & 0xffff0000u); }
; __device__ __forceinline__ void pool_phase(LAS unsigned char* lds, const bf16_t* PROJ, const bf16_t* PW, const float* pscale, bf16_t* Y, float* SS, int bx, int G) {
;     ...
;             for (int j = 1; j < 16; ++j) if (j < w) { s0 += bf_lo(xr[15 - j]); s1 += bf_hi(xr[15 - j]); }
; #pragma unroll
;             for (int tt = 0; tt < 16; ++tt) { const int t = t_start + tt; const unsigned x = xr[tt + 15]; const float x0 = bf_lo(x), x1 = bf_hi(x);
;                 s0 += x0; s1 += x1; const int pos = pos0 + t; const float rc = __builtin_amdgcn_rcpf((float)((pos + 1 < w) ? (pos + 1) : w));
;                 const float d0 = s0 * rc - x0, d1 = s1 * rc - x1;
;                 *(LAS unsigned*)(lds + PL_DT + t * PL_DROW + cp * 4) = cvt_pk_bf16(d0, d1);
;                 const unsigned xo = (w == 2) ? xr[tt + 14] : (w == 4) ? xr[tt + 12] : (w == 8) ? xr[tt + 8] : xr[tt]; s0 -= bf_lo(xo); s1 -= bf_hi(xo); }
	v_lshlrev_b32_e32 v147, 16, v150
	v_sub_f32_e32 v153, v153, v146
	v_rcp_iflag_f32_e32 v154, v154
	v_and_b32_e32 v146, 0xffff0000, v150
	v_add_f32_e32 v150, v152, v147
	v_add_f32_e32 v152, v153, v146
	v_fma_f32 v153, v154, v150, -v147
	v_fma_f32 v154, v154, v152, -v146
	v_cvt_pk_bf16_f32 v153, v153, v154
	ds_write_b32 v194, v153 offset:43072
	v_mov_b64_e32 v[148:149], v[144:145]
	v_mov_b64_e32 v[148:149], v[136:137]
	v_add_u32_e32 v153, s72, v164
	v_min_i32_e32 v153, s78, v153
	v_cvt_f32_i32_e32 v153, v153
	v_sub_f32_e32 v150, v150, v149
	v_lshlrev_b32_e32 v149, 16, v151
	v_sub_f32_e32 v152, v152, v148
	v_rcp_iflag_f32_e32 v153, v153
	v_and_b32_e32 v148, 0xffff0000, v151
	v_add_f32_e32 v150, v150, v149
	v_add_f32_e32 v151, v152, v148
	v_fma_f32 v152, v153, v150, -v149
	v_fma_f32 v153, v153, v151, -v148
	v_cvt_pk_bf16_f32 v152, v152, v153
	ds_write_b32 v194, v152 offset:43600
	v_mov_b64_e32 v[142:143], v[146:147]
	v_mov_b64_e32 v[142:143], v[140:141]
	v_add_u32_e32 v152, s72, v165
	v_min_i32_e32 v152, s78, v152
	v_cvt_f32_i32_e32 v152, v152
	v_sub_f32_e32 v150, v150, v143
	s_waitcnt lgkmcnt(10)
	v_lshlrev_b32_e32 v143, 16, v126
	v_sub_f32_e32 v151, v151, v142
	v_rcp_iflag_f32_e32 v152, v152
	v_and_b32_e32 v142, 0xffff0000, v126
	v_add_f32_e32 v126, v150, v143
	v_add_f32_e32 v150, v151, v142
	v_fma_f32 v151, v152, v126, -v143
	v_fma_f32 v152, v152, v150, -v142
	v_cvt_pk_bf16_f32 v151, v151, v152
	ds_write_b32 v194, v151 offset:44128
	v_mov_b64_e32 v[138:139], v[148:149]
	v_mov_b64_e32 v[138:139], v[144:145]
	v_add_u32_e32 v151, s72, v166
	v_min_i32_e32 v151, s78, v151
	v_cvt_f32_i32_e32 v151, v151
	v_sub_f32_e32 v126, v126, v139
	v_lshlrev_b32_e32 v139, 16, v127
	v_sub_f32_e32 v150, v150, v138
	v_rcp_iflag_f32_e32 v151, v151
	v_and_b32_e32 v138, 0xffff0000, v127
	v_add_f32_e32 v126, v126, v139
	v_add_f32_e32 v127, v150, v138
	v_fma_f32 v150, v151, v126, -v139
	v_fma_f32 v151, v151, v127, -v138
	v_cvt_pk_bf16_f32 v150, v150, v151
	ds_write_b32 v194, v150 offset:44656
	v_mov_b64_e32 v[124:125], v[142:143]
	v_mov_b64_e32 v[124:125], v[146:147]
	v_add_u32_e32 v128, s72, v167
	v_min_i32_e32 v128, s78, v128
	v_cvt_f32_i32_e32 v128, v128
	v_sub_f32_e32 v126, v126, v125
	s_waitcnt lgkmcnt(11)
	v_lshlrev_b32_e32 v125, 16, v118
	v_sub_f32_e32 v127, v127, v124
	v_rcp_iflag_f32_e32 v128, v128
	v_and_b32_e32 v124, 0xffff0000, v118
	v_add_f32_e32 v118, v126, v125
	v_add_f32_e32 v126, v127, v124
	v_fma_f32 v127, v128, v118, -v125
	v_fma_f32 v128, v128, v126, -v124
	v_cvt_pk_bf16_f32 v127, v127, v128
	ds_write_b32 v194, v127 offset:45184
	v_mov_b64_e32 v[136:137], v[138:139]
	v_mov_b64_e32 v[136:137], v[148:149]
	v_add_u32_e32 v122, s72, v168
	v_min_i32_e32 v122, s78, v122
	v_cvt_f32_i32_e32 v122, v122
	v_sub_f32_e32 v118, v118, v137
	v_lshlrev_b32_e32 v123, 16, v119
	v_sub_f32_e32 v126, v126, v136
	v_rcp_iflag_f32_e32 v127, v122
	v_and_b32_e32 v122, 0xffff0000, v119
	v_add_f32_e32 v118, v118, v123
	v_add_f32_e32 v119, v126, v122
	v_fma_f32 v126, v127, v118, -v123
	v_fma_f32 v127, v127, v119, -v122
	v_cvt_pk_bf16_f32 v126, v126, v127
	ds_write_b32 v194, v126 offset:45712
	v_mov_b64_e32 v[140:141], v[124:125]
	v_mov_b64_e32 v[140:141], v[142:143]
	v_add_u32_e32 v120, s72, v169
	v_min_i32_e32 v120, s78, v120
	v_cvt_f32_i32_e32 v120, v120
	v_sub_f32_e32 v121, v118, v141
	v_sub_f32_e32 v126, v119, v140
	s_waitcnt lgkmcnt(12)
	v_lshlrev_b32_e32 v119, 16, v114
	v_rcp_iflag_f32_e32 v127, v120
	v_and_b32_e32 v118, 0xffff0000, v114
	v_add_f32_e32 v114, v121, v119
	v_add_f32_e32 v120, v126, v118
	v_fma_f32 v121, v127, v114, -v119
	v_fma_f32 v126, v127, v120, -v118
	v_cvt_pk_bf16_f32 v121, v121, v126
	ds_write_b32 v194, v121 offset:46240
	v_mov_b64_e32 v[144:145], v[122:123]
	v_mov_b64_e32 v[144:145], v[138:139]
	v_add_u32_e32 v116, s72, v170
	v_min_i32_e32 v116, s78, v116
	v_cvt_f32_i32_e32 v116, v116
	v_sub_f32_e32 v114, v114, v145
	v_lshlrev_b32_e32 v117, 16, v115
	v_sub_f32_e32 v120, v120, v144
	v_rcp_iflag_f32_e32 v121, v116
	v_and_b32_e32 v116, 0xffff0000, v115
	v_add_f32_e32 v114, v114, v117
	v_add_f32_e32 v115, v120, v116
	v_fma_f32 v120, v121, v114, -v117
	v_fma_f32 v121, v121, v115, -v116
	v_cvt_pk_bf16_f32 v120, v120, v121
	ds_write_b32 v194, v120 offset:46768
	v_mov_b64_e32 v[146:147], v[118:119]
	v_mov_b64_e32 v[146:147], v[124:125]
	v_add_u32_e32 v112, s72, v171
	v_min_i32_e32 v112, s78, v112
	v_cvt_f32_i32_e32 v112, v112
	v_sub_f32_e32 v114, v114, v147
	s_waitcnt lgkmcnt(13)
	v_lshlrev_b32_e32 v113, 16, v108
	v_sub_f32_e32 v115, v115, v146
	v_rcp_iflag_f32_e32 v120, v112
	v_and_b32_e32 v112, 0xffff0000, v108
	v_add_f32_e32 v108, v114, v113
	v_add_f32_e32 v114, v115, v112
	v_fma_f32 v115, v120, v108, -v113
	v_fma_f32 v120, v120, v114, -v112
	v_cvt_pk_bf16_f32 v115, v115, v120
	ds_write_b32 v194, v115 offset:47296
	v_mov_b64_e32 v[148:149], v[116:117]
	v_mov_b64_e32 v[148:149], v[122:123]
	v_add_u32_e32 v110, s72, v172
	v_min_i32_e32 v110, s78, v110
	v_cvt_f32_i32_e32 v110, v110
	v_sub_f32_e32 v108, v108, v149
	v_lshlrev_b32_e32 v111, 16, v109
	v_sub_f32_e32 v114, v114, v148
	v_rcp_iflag_f32_e32 v115, v110
	v_and_b32_e32 v110, 0xffff0000, v109
	v_add_f32_e32 v108, v108, v111
	v_add_f32_e32 v109, v114, v110
	v_fma_f32 v114, v115, v108, -v111
	v_fma_f32 v115, v115, v109, -v110
	v_cvt_pk_bf16_f32 v114, v114, v115
	ds_write_b32 v194, v114 offset:47824
	v_mov_b64_e32 v[142:143], v[118:119]
	v_add_u32_e32 v106, s72, v173
	v_min_i32_e32 v106, s78, v106
	v_cvt_f32_i32_e32 v106, v106
	v_sub_f32_e32 v107, v108, v143
	v_sub_f32_e32 v108, v109, v142
	s_waitcnt lgkmcnt(14)
	v_lshlrev_b32_e32 v109, 16, v102
	v_rcp_iflag_f32_e32 v112, v106
	v_and_b32_e32 v113, 0xffff0000, v102
	v_add_f32_e32 v102, v107, v109
	v_add_f32_e32 v106, v108, v113
	v_fma_f32 v107, v112, v102, -v109
	v_fma_f32 v108, v112, v106, -v113
	v_cvt_pk_bf16_f32 v107, v107, v108
	ds_write_b32 v194, v107 offset:48352
	v_mov_b64_e32 v[138:139], v[116:117]
	v_add_u32_e32 v104, s72, v174
	v_min_i32_e32 v104, s78, v104
	v_cvt_f32_i32_e32 v104, v104
	v_sub_f32_e32 v102, v102, v139
	v_sub_f32_e32 v105, v106, v138
	v_lshlrev_b32_e32 v106, 16, v103
	v_rcp_iflag_f32_e32 v104, v104
	v_and_b32_e32 v103, 0xffff0000, v103
	v_add_f32_e32 v102, v102, v106
	v_add_f32_e32 v105, v105, v103
	v_fma_f32 v102, v104, v102, -v106
	v_fma_f32 v103, v104, v105, -v103
	v_cvt_pk_bf16_f32 v102, v102, v103
	ds_write_b32 v190, v102 offset:40960
	s_waitcnt lgkmcnt(0)
	s_branch .Lpool_sw_join
; __device__ __forceinline__ unsigned cvt_pk_bf16(float lo, float hi) { unsigned r; asm volatile("v_cvt_pk_bf16_f32 %0, %1, %2" : "=v"(r) : "v"(lo), "v"(hi)); return r; }
; #define LAS __attribute__((address_space(3)))
; __device__ __forceinline__ float bf_lo(unsigned u) { return __uint_as_float(u << 16); }
; __device__ __forceinline__ float bf_hi(unsigned u) { return __uint_as_float(u & 0xffff0000u); }
; __device__ __forceinline__ void pool_phase(LAS unsigned char* lds, const bf16_t* PROJ, const bf16_t* PW, const float* pscale, bf16_t* Y, float* SS, int bx, int G) {
;     ...
;             unsigned xr[31];
; #pragma unroll
;             for (int r = 0; r < 31; ++r) xr[r] = xs[(t_start + r + 1) * 128];
;             float s0 = 0.f, s1 = 0.f;
; #pragma unroll
;             for (int j = 1; j < 16; ++j) if (j < w) { s0 += bf_lo(xr[15 - j]); s1 += bf_hi(xr[15 - j]); }
; #pragma unroll
;             for (int tt = 0; tt < 16; ++tt) { const int t = t_start + tt; const unsigned x = xr[tt + 15]; const float x0 = bf_lo(x), x1 = bf_hi(x);
;                 s0 += x0; s1 += x1; const int pos = pos0 + t; const float rc = __builtin_amdgcn_rcpf((float)((pos + 1 < w) ? (pos + 1) : w));
;                 const float d0 = s0 * rc - x0, d1 = s1 * rc - x1;
;                 *(LAS unsigned*)(lds + PL_DT + t * PL_DROW + cp * 4) = cvt_pk_bf16(d0, d1);
;                 const unsigned xo = (w == 2) ? xr[tt + 14] : (w == 4) ? xr[tt + 12] : (w == 8) ? xr[tt + 8] : xr[tt]; s0 -= bf_lo(xo); s1 -= bf_hi(xo); }
.Lpool_g2:
	ds_read2st64_b32 v[124:125], v188 offset0:2 offset1:4
	ds_read2st64_b32 v[136:137], v188 offset0:6 offset1:8
	ds_read2st64_b32 v[140:141], v188 offset0:10 offset1:12
	ds_read2st64_b32 v[138:139], v188 offset0:14 offset1:16
	ds_read2st64_b32 v[122:123], v188 offset0:18 offset1:20
	ds_read2st64_b32 v[116:117], v188 offset0:22 offset1:24
	ds_read2st64_b32 v[110:111], v188 offset0:26 offset1:28
	ds_read2st64_b32 v[154:155], v188 offset0:30 offset1:34
	ds_read_b32 v181, v189 offset:512
	ds_read2st64_b32 v[152:153], v188 offset0:36 offset1:38
	ds_read2st64_b32 v[150:151], v188 offset0:40 offset1:42
	ds_read2st64_b32 v[126:127], v188 offset0:44 offset1:46
	ds_read2st64_b32 v[118:119], v188 offset0:48 offset1:50
	ds_read2st64_b32 v[114:115], v188 offset0:52 offset1:54
	ds_read2st64_b32 v[108:109], v188 offset0:56 offset1:58
	ds_read2st64_b32 v[102:103], v188 offset0:60 offset1:62
	s_waitcnt lgkmcnt(8)
	v_lshlrev_b32_e32 v105, 16, v154
	v_and_b32_e32 v104, 0xffff0000, v154
	v_add_f32_e32 v112, 0, v105
	v_add_f32_e32 v113, 0, v104
	v_lshlrev_b32_e32 v107, 16, v111
	v_and_b32_e32 v106, 0xffff0000, v111
	v_add_f32_e32 v120, v112, v107
	v_add_f32_e32 v121, v113, v106
	v_lshlrev_b32_e32 v111, 16, v110
	v_and_b32_e32 v110, 0xffff0000, v110
	s_add_i32 s88, s76, s79
	v_add_f32_e32 v120, v120, v111
	v_add_f32_e32 v121, v121, v110
	s_ashr_i32 s70, s88, 31
	v_cndmask_b32_e64 v128, v121, v113, s[10:11]
	v_cndmask_b32_e64 v129, v120, v112, s[10:11]
	v_lshlrev_b32_e32 v113, 16, v117
	v_and_b32_e32 v112, 0xffff0000, v117
	s_lshr_b32 s70, s70, 20
	v_add_f32_e32 v120, v129, v113
	v_add_f32_e32 v121, v128, v112
	v_lshlrev_b32_e32 v117, 16, v116
	v_and_b32_e32 v116, 0xffff0000, v116
	s_add_i32 s70, s88, s70
	v_add_f32_e32 v142, v120, v117
	v_add_f32_e32 v143, v121, v116
	v_lshlrev_b32_e32 v121, 16, v123
	v_and_b32_e32 v120, 0xffff0000, v123
	s_and_b32 s70, s70, 0xfffff000
	v_add_f32_e32 v142, v142, v121
	v_add_f32_e32 v143, v143, v120
	v_lshlrev_b32_e32 v123, 16, v122
	v_and_b32_e32 v122, 0xffff0000, v122
	s_sub_i32 s70, s88, s70
	v_add_f32_e32 v142, v142, v123
	v_add_f32_e32 v143, v143, v122
	v_cndmask_b32_e64 v154, v128, v143, s[12:13]
	v_cndmask_b32_e64 v195, v129, v142, s[12:13]
	v_lshlrev_b32_e32 v129, 16, v139
	v_and_b32_e32 v128, 0xffff0000, v139
	s_or_b32 s72, s70, 1
	v_lshlrev_b32_e32 v139, 16, v138
	v_and_b32_e32 v138, 0xffff0000, v138
	v_lshlrev_b32_e32 v143, 16, v141
	v_and_b32_e32 v142, 0xffff0000, v141
	v_lshlrev_b32_e32 v149, 16, v140
	v_and_b32_e32 v148, 0xffff0000, v140
	v_lshlrev_b32_e32 v147, 16, v137
	v_and_b32_e32 v146, 0xffff0000, v137
	v_lshlrev_b32_e32 v145, 16, v136
	v_and_b32_e32 v144, 0xffff0000, v136
	v_lshlrev_b32_e32 v141, 16, v125
	v_and_b32_e32 v140, 0xffff0000, v125
	v_lshlrev_b32_e32 v137, 16, v124
	v_and_b32_e32 v136, 0xffff0000, v124
	s_waitcnt lgkmcnt(7)
	v_lshlrev_b32_e32 v125, 16, v181
	v_and_b32_e32 v124, 0xffff0000, v181
	v_add_f32_e32 v181, v195, v129
	v_add_f32_e32 v196, v154, v128
	v_add_u32_e32 v197, s72, v1
	v_add_f32_e32 v181, v181, v139
	v_add_f32_e32 v196, v196, v138
	v_min_i32_e32 v197, s78, v197
	v_add_f32_e32 v181, v181, v143
	v_add_f32_e32 v196, v196, v142
	v_cvt_f32_i32_e32 v197, v197
	v_add_f32_e32 v181, v181, v149
	v_add_f32_e32 v196, v196, v148
	v_add_f32_e32 v181, v181, v147
	v_add_f32_e32 v196, v196, v146
	v_add_f32_e32 v181, v181, v145
	v_add_f32_e32 v196, v196, v144
	v_add_f32_e32 v181, v181, v141
	v_add_f32_e32 v196, v196, v140
	v_rcp_iflag_f32_e32 v197, v197
	v_add_f32_e32 v181, v181, v137
	v_add_f32_e32 v196, v196, v136
	v_cndmask_b32_e64 v196, v154, v196, s[14:15]
	v_cndmask_b32_e64 v154, v195, v181, s[14:15]
	v_add_f32_e32 v154, v154, v125
	v_add_f32_e32 v195, v196, v124
	v_fma_f32 v181, v197, v154, -v125
	v_fma_f32 v196, v197, v195, -v124
	v_cvt_pk_bf16_f32 v181, v181, v196
	ds_write_b32 v194, v181 offset:40960
	v_mov_b64_e32 v[136:137], v[122:123]
	v_add_u32_e32 v181, s72, v160
	v_min_i32_e32 v181, s78, v181
	v_cvt_f32_i32_e32 v181, v181
	v_sub_f32_e32 v154, v154, v137
	v_sub_f32_e32 v195, v195, v136
	v_lshlrev_b32_e32 v137, 16, v155
	v_rcp_iflag_f32_e32 v181, v181
	v_and_b32_e32 v136, 0xffff0000, v155
	v_add_f32_e32 v154, v154, v137
	v_add_f32_e32 v155, v195, v136
	v_fma_f32 v195, v181, v154, -v137
	v_fma_f32 v181, v181, v155, -v136
	v_cvt_pk_bf16_f32 v181, v195, v181
	ds_write_b32 v194, v181 offset:41488
	v_mov_b64_e32 v[140:141], v[120:121]
	v_add_u32_e32 v181, s72, v161
	v_min_i32_e32 v181, s78, v181
	v_cvt_f32_i32_e32 v181, v181
	v_sub_f32_e32 v154, v154, v141
	s_waitcnt lgkmcnt(8)
	v_lshlrev_b32_e32 v141, 16, v152
	v_sub_f32_e32 v155, v155, v140
	v_rcp_iflag_f32_e32 v181, v181
	v_and_b32_e32 v140, 0xffff0000, v152
	v_add_f32_e32 v152, v154, v141
	v_add_f32_e32 v154, v155, v140
	v_fma_f32 v155, v181, v152, -v141
	v_fma_f32 v181, v181, v154, -v140
	v_cvt_pk_bf16_f32 v155, v155, v181
	ds_write_b32 v194, v155 offset:42016
	v_mov_b64_e32 v[144:145], v[116:117]
	v_add_u32_e32 v155, s72, v162
	v_min_i32_e32 v155, s78, v155
	v_cvt_f32_i32_e32 v155, v155
	v_sub_f32_e32 v152, v152, v145
	v_lshlrev_b32_e32 v145, 16, v153
	v_sub_f32_e32 v154, v154, v144
	v_rcp_iflag_f32_e32 v155, v155
	v_and_b32_e32 v144, 0xffff0000, v153
	v_add_f32_e32 v152, v152, v145
	v_add_f32_e32 v153, v154, v144
	v_fma_f32 v154, v155, v152, -v145
	v_fma_f32 v155, v155, v153, -v144
	v_cvt_pk_bf16_f32 v154, v154, v155
	ds_write_b32 v194, v154 offset:42544
	v_mov_b64_e32 v[146:147], v[112:113]
	v_add_u32_e32 v154, s72, v163
	v_min_i32_e32 v154, s78, v154
	v_cvt_f32_i32_e32 v154, v154
	v_sub_f32_e32 v152, v152, v147
	s_waitcnt lgkmcnt(9)
; __device__ __forceinline__ unsigned cvt_pk_bf16(float lo, float hi) { unsigned r; asm volatile("v_cvt_pk_bf16_f32 %0, %1, %2" : "=v"(r) : "v"(lo), "v"(hi)); return r; }
; #define LAS __attribute__((address_space(3)))
; __device__ __forceinline__ float bf_lo(unsigned u) { return __uint_as_float(u << 16); }
; __device__ __forceinline__ float bf_hi(unsigned u) { return __uint_as_float(u & 0xffff0000u); }
; __device__ __forceinline__ void pool_phase(LAS unsigned char* lds, const bf16_t* PROJ, const bf16_t* PW, const float* pscale, bf16_t* Y, float* SS, int bx, int G) {
;     ...
;             for (int j = 1; j < 16; ++j) if (j < w) { s0 += bf_lo(xr[15 - j]); s1 += bf_hi(xr[15 - j]); }
; #pragma unroll
;             for (int tt = 0; tt < 16; ++tt) { const int t = t_start + tt; const unsigned x = xr[tt + 15]; const float x0 = bf_lo(x), x1 = bf_hi(x);
;                 s0 += x0; s1 += x1; const int pos = pos0 + t; const float rc = __builtin_amdgcn_rcpf((float)((pos + 1 < w) ? (pos + 1) : w));
;                 const float d0 = s0 * rc - x0, d1 = s1 * rc - x1;
;                 *(LAS unsigned*)(lds + PL_DT + t * PL_DROW + cp * 4) = cvt_pk_bf16(d0, d1);
;                 const unsigned xo = (w == 2) ? xr[tt + 14] : (w == 4) ? xr[tt + 12] : (w == 8) ? xr[tt + 8] : xr[tt]; s0 -= bf_lo(xo); s1 -= bf_hi(xo); }
	v_lshlrev_b32_e32 v147, 16, v150
	v_sub_f32_e32 v153, v153, v146
	v_rcp_iflag_f32_e32 v154, v154
	v_and_b32_e32 v146, 0xffff0000, v150
	v_add_f32_e32 v150, v152, v147
	v_add_f32_e32 v152, v153, v146
	v_fma_f32 v153, v154, v150, -v147
	v_fma_f32 v154, v154, v152, -v146
	v_cvt_pk_bf16_f32 v153, v153, v154
	ds_write_b32 v194, v153 offset:43072
	v_mov_b64_e32 v[148:149], v[110:111]
	v_add_u32_e32 v153, s72, v164
	v_min_i32_e32 v153, s78, v153
	v_cvt_f32_i32_e32 v153, v153
	v_sub_f32_e32 v150, v150, v149
	v_lshlrev_b32_e32 v149, 16, v151
	v_sub_f32_e32 v152, v152, v148
	v_rcp_iflag_f32_e32 v153, v153
	v_and_b32_e32 v148, 0xffff0000, v151
	v_add_f32_e32 v150, v150, v149
	v_add_f32_e32 v151, v152, v148
	v_fma_f32 v152, v153, v150, -v149
	v_fma_f32 v153, v153, v151, -v148
	v_cvt_pk_bf16_f32 v152, v152, v153
	ds_write_b32 v194, v152 offset:43600
	v_mov_b64_e32 v[142:143], v[106:107]
	v_add_u32_e32 v152, s72, v165
	v_min_i32_e32 v152, s78, v152
	v_cvt_f32_i32_e32 v152, v152
	v_sub_f32_e32 v150, v150, v143
	s_waitcnt lgkmcnt(10)
	v_lshlrev_b32_e32 v143, 16, v126
	v_sub_f32_e32 v151, v151, v142
	v_rcp_iflag_f32_e32 v152, v152
	v_and_b32_e32 v142, 0xffff0000, v126
	v_add_f32_e32 v126, v150, v143
	v_add_f32_e32 v150, v151, v142
	v_fma_f32 v151, v152, v126, -v143
	v_fma_f32 v152, v152, v150, -v142
	v_cvt_pk_bf16_f32 v151, v151, v152
	ds_write_b32 v194, v151 offset:44128
	v_mov_b64_e32 v[138:139], v[104:105]
	v_add_u32_e32 v151, s72, v166
	v_min_i32_e32 v151, s78, v151
	v_cvt_f32_i32_e32 v151, v151
	v_sub_f32_e32 v126, v126, v139
	v_lshlrev_b32_e32 v139, 16, v127
	v_sub_f32_e32 v150, v150, v138
	v_rcp_iflag_f32_e32 v151, v151
	v_and_b32_e32 v138, 0xffff0000, v127
	v_add_f32_e32 v126, v126, v139
	v_add_f32_e32 v127, v150, v138
	v_fma_f32 v150, v151, v126, -v139
	v_fma_f32 v151, v151, v127, -v138
	v_cvt_pk_bf16_f32 v150, v150, v151
	ds_write_b32 v194, v150 offset:44656
	v_add_u32_e32 v128, s72, v167
	v_min_i32_e32 v128, s78, v128
	v_cvt_f32_i32_e32 v128, v128
	v_sub_f32_e32 v126, v126, v125
	s_waitcnt lgkmcnt(11)
	v_lshlrev_b32_e32 v125, 16, v118
	v_sub_f32_e32 v127, v127, v124
	v_rcp_iflag_f32_e32 v128, v128
	v_and_b32_e32 v124, 0xffff0000, v118
	v_add_f32_e32 v118, v126, v125
	v_add_f32_e32 v126, v127, v124
	v_fma_f32 v127, v128, v118, -v125
	v_fma_f32 v128, v128, v126, -v124
	v_cvt_pk_bf16_f32 v127, v127, v128
	ds_write_b32 v194, v127 offset:45184
	v_add_u32_e32 v122, s72, v168
	v_min_i32_e32 v122, s78, v122
	v_cvt_f32_i32_e32 v122, v122
	v_sub_f32_e32 v118, v118, v137
	v_lshlrev_b32_e32 v123, 16, v119
	v_sub_f32_e32 v126, v126, v136
	v_rcp_iflag_f32_e32 v127, v122
	v_and_b32_e32 v122, 0xffff0000, v119
	v_add_f32_e32 v118, v118, v123
	v_add_f32_e32 v119, v126, v122
	v_fma_f32 v126, v127, v118, -v123
	v_fma_f32 v127, v127, v119, -v122
	v_cvt_pk_bf16_f32 v126, v126, v127
	ds_write_b32 v194, v126 offset:45712
	v_add_u32_e32 v120, s72, v169
	v_min_i32_e32 v120, s78, v120
	v_cvt_f32_i32_e32 v120, v120
	v_sub_f32_e32 v121, v118, v141
	v_sub_f32_e32 v126, v119, v140
	s_waitcnt lgkmcnt(12)
	v_lshlrev_b32_e32 v119, 16, v114
	v_rcp_iflag_f32_e32 v127, v120
	v_and_b32_e32 v118, 0xffff0000, v114
	v_add_f32_e32 v114, v121, v119
	v_add_f32_e32 v120, v126, v118
	v_fma_f32 v121, v127, v114, -v119
	v_fma_f32 v126, v127, v120, -v118
	v_cvt_pk_bf16_f32 v121, v121, v126
	ds_write_b32 v194, v121 offset:46240
	v_add_u32_e32 v116, s72, v170
	v_min_i32_e32 v116, s78, v116
	v_cvt_f32_i32_e32 v116, v116
	v_sub_f32_e32 v114, v114, v145
	v_lshlrev_b32_e32 v117, 16, v115
	v_sub_f32_e32 v120, v120, v144
	v_rcp_iflag_f32_e32 v121, v116
	v_and_b32_e32 v116, 0xffff0000, v115
	v_add_f32_e32 v114, v114, v117
	v_add_f32_e32 v115, v120, v116
	v_fma_f32 v120, v121, v114, -v117
	v_fma_f32 v121, v121, v115, -v116
	v_cvt_pk_bf16_f32 v120, v120, v121
	ds_write_b32 v194, v120 offset:46768
	v_add_u32_e32 v112, s72, v171
	v_min_i32_e32 v112, s78, v112
	v_cvt_f32_i32_e32 v112, v112
	v_sub_f32_e32 v114, v114, v147
	s_waitcnt lgkmcnt(13)
	v_lshlrev_b32_e32 v113, 16, v108
	v_sub_f32_e32 v115, v115, v146
	v_rcp_iflag_f32_e32 v120, v112
	v_and_b32_e32 v112, 0xffff0000, v108
	v_add_f32_e32 v108, v114, v113
	v_add_f32_e32 v114, v115, v112
	v_fma_f32 v115, v120, v108, -v113
	v_fma_f32 v120, v120, v114, -v112
	v_cvt_pk_bf16_f32 v115, v115, v120
	ds_write_b32 v194, v115 offset:47296
	v_add_u32_e32 v110, s72, v172
	v_min_i32_e32 v110, s78, v110
	v_cvt_f32_i32_e32 v110, v110
	v_sub_f32_e32 v108, v108, v149
	v_lshlrev_b32_e32 v111, 16, v109
	v_sub_f32_e32 v114, v114, v148
	v_rcp_iflag_f32_e32 v115, v110
	v_and_b32_e32 v110, 0xffff0000, v109
	v_add_f32_e32 v108, v108, v111
	v_add_f32_e32 v109, v114, v110
	v_fma_f32 v114, v115, v108, -v111
	v_fma_f32 v115, v115, v109, -v110
	v_cvt_pk_bf16_f32 v114, v114, v115
	ds_write_b32 v194, v114 offset:47824
	v_add_u32_e32 v106, s72, v173
	v_min_i32_e32 v106, s78, v106
	v_cvt_f32_i32_e32 v106, v106
	v_sub_f32_e32 v107, v108, v143
	v_sub_f32_e32 v108, v109, v142
	s_waitcnt lgkmcnt(14)
	v_lshlrev_b32_e32 v109, 16, v102
	v_rcp_iflag_f32_e32 v112, v106
	v_and_b32_e32 v113, 0xffff0000, v102
	v_add_f32_e32 v102, v107, v109
	v_add_f32_e32 v106, v108, v113
	v_fma_f32 v107, v112, v102, -v109
	v_fma_f32 v108, v112, v106, -v113
	v_cvt_pk_bf16_f32 v107, v107, v108
	ds_write_b32 v194, v107 offset:48352
	v_add_u32_e32 v104, s72, v174
	v_min_i32_e32 v104, s78, v104
	v_cvt_f32_i32_e32 v104, v104
	v_sub_f32_e32 v102, v102, v139
	v_sub_f32_e32 v105, v106, v138
	v_lshlrev_b32_e32 v106, 16, v103
	v_rcp_iflag_f32_e32 v104, v104
	v_and_b32_e32 v103, 0xffff0000, v103
	v_add_f32_e32 v102, v102, v106
	v_add_f32_e32 v105, v105, v103
	v_fma_f32 v102, v104, v102, -v106
	v_fma_f32 v103, v104, v105, -v103
	v_cvt_pk_bf16_f32 v102, v102, v103
	ds_write_b32 v190, v102 offset:40960
	s_waitcnt lgkmcnt(0)
	s_branch .Lpool_sw_join
; #define LAS __attribute__((address_space(3)))
; #define MFMA16(a, b, c) __builtin_amdgcn_mfma_f32_16x16x32_bf16((a), (b), (c), 0, 0, 0)
; __device__ __forceinline__ void pool_phase(LAS unsigned char* lds, const bf16_t* PROJ, const bf16_t* PW, const float* pscale, bf16_t* Y, float* SS, int bx, int G) {
;     ...
;         __syncthreads();
;         f32x4 acc[2][4];
; #pragma unroll
;         for (int j = 0; j < 2; ++j)
; #pragma unroll
;             for (int m = 0; m < 4; ++m) acc[j][m] = (f32x4){0.f, 0.f, 0.f, 0.f};
;         { bf16x8 dfb[2][4];
; #pragma unroll
;           for (int m = 0; m < 4; ++m) dfb[0][m] = *(const LAS bf16x8*)(lds + PL_DT + (16 * m + fr) * PL_DROW + (8 * fq) * 2);
; #pragma unroll
;           for (int ks = 0; ks < 8; ++ks) {
;               if (ks + 1 < 8) {
; #pragma unroll
;                   for (int m = 0; m < 4; ++m) dfb[(ks + 1) & 1][m] = *(const LAS bf16x8*)(lds + PL_DT + (16 * m + fr) * PL_DROW + (32 * (ks + 1) + 8 * fq) * 2); }
; #pragma unroll
;               for (int m = 0; m < 4; ++m)
; #pragma unroll
;                   for (int j = 0; j < 2; ++j) acc[j][m] = MFMA16(wf[j][ks], dfb[ks & 1][m], acc[j][m]);
;           } }
;         const int cb = g * 256 + 32 * wid + 8 * fq; const f32x4 sc0 = *(const f32x4*)(pscale + cb), sc1 = *(const f32x4*)(pscale + cb + 4);
.Lpool_sw_join:
	s_barrier
	ds_read_b128 v[102:105], v191 offset:40960
	ds_read_b128 v[106:109], v191 offset:41024
	ds_read_b128 v[114:117], v191 offset:49408
	ds_read_b128 v[118:121], v191 offset:49472
	ds_read_b128 v[126:129], v191 offset:57856
	ds_read_b128 v[136:139], v191 offset:57920
	ds_read_b128 v[144:147], v192 offset:40960
	ds_read_b128 v[148:151], v192 offset:41024
	s_waitcnt lgkmcnt(7)
	v_mfma_f32_16x16x32_bf16 v[110:113], v[2:5], v[102:105], 0
	s_waitcnt vmcnt(3)
	v_lshlrev_b32_e32 v181, 16, v98
	v_and_b32_e32 v98, 0xffff0000, v98
	s_ashr_i32 s70, s86, 1
	v_mfma_f32_16x16x32_bf16 v[102:105], v[34:37], v[102:105], 0
	s_mul_hi_i32 s71, s70, 48
	s_mul_i32 s70, s70, 48
	s_add_u32 s70, s70, s80
	s_waitcnt lgkmcnt(5)
	v_mfma_f32_16x16x32_bf16 v[122:125], v[2:5], v[114:117], 0
	s_addc_u32 s71, s71, s81
	s_lshl_b64 s[70:71], s[70:71], 14
	s_add_u32 s70, s44, s70
	v_mfma_f32_16x16x32_bf16 v[114:117], v[34:37], v[114:117], 0
	s_addc_u32 s71, s45, s71
	s_lshr_b32 s72, s88, 3
	s_waitcnt lgkmcnt(3)
	v_mfma_f32_16x16x32_bf16 v[140:143], v[2:5], v[126:129], 0
	v_mfma_f32_16x16x32_bf16 v[126:129], v[34:37], v[126:129], 0
	s_waitcnt lgkmcnt(1)
	v_mfma_f32_16x16x32_bf16 v[152:155], v[2:5], v[144:147], 0
	v_mfma_f32_16x16x32_bf16 v[144:147], v[34:37], v[144:147], 0
	v_mfma_f32_16x16x32_bf16 v[110:113], v[6:9], v[106:109], v[110:113]
	v_mfma_f32_16x16x32_bf16 v[102:105], v[38:41], v[106:109], v[102:105]
	v_mfma_f32_16x16x32_bf16 v[106:109], v[6:9], v[118:121], v[122:125]
	v_mfma_f32_16x16x32_bf16 v[114:117], v[38:41], v[118:121], v[114:117]
	v_mfma_f32_16x16x32_bf16 v[118:121], v[6:9], v[136:139], v[140:143]
	v_mfma_f32_16x16x32_bf16 v[122:125], v[38:41], v[136:139], v[126:129]
	s_waitcnt lgkmcnt(0)
	v_mfma_f32_16x16x32_bf16 v[136:139], v[38:41], v[148:151], v[144:147]
	ds_read_b128 v[140:143], v191 offset:41088
	s_nop 1
	ds_read_b128 v[144:147], v191 offset:41152
	v_mfma_f32_16x16x32_bf16 v[126:129], v[6:9], v[148:151], v[152:155]
	s_waitcnt lgkmcnt(1)
	v_mfma_f32_16x16x32_bf16 v[110:113], v[10:13], v[140:143], v[110:113]
	v_mfma_f32_16x16x32_bf16 v[102:105], v[42:45], v[140:143], v[102:105]
	ds_read_b128 v[140:143], v191 offset:49536
	ds_read_b128 v[148:151], v191 offset:49600
	s_waitcnt lgkmcnt(1)
	v_mfma_f32_16x16x32_bf16 v[106:109], v[10:13], v[140:143], v[106:109]
	v_mfma_f32_16x16x32_bf16 v[114:117], v[42:45], v[140:143], v[114:117]
	ds_read_b128 v[140:143], v191 offset:57984
	ds_read_b128 v[152:155], v191 offset:58048
	s_waitcnt lgkmcnt(1)
	v_mfma_f32_16x16x32_bf16 v[118:121], v[10:13], v[140:143], v[118:121]
	v_mfma_f32_16x16x32_bf16 v[122:125], v[42:45], v[140:143], v[122:125]
	ds_read_b128 v[140:143], v192 offset:41088
	ds_read_b128 v[196:199], v192 offset:41152
	s_waitcnt lgkmcnt(1)
	v_mfma_f32_16x16x32_bf16 v[126:129], v[10:13], v[140:143], v[126:129]
	v_mfma_f32_16x16x32_bf16 v[136:139], v[42:45], v[140:143], v[136:139]
	v_mfma_f32_16x16x32_bf16 v[110:113], v[14:17], v[144:147], v[110:113]
	v_mfma_f32_16x16x32_bf16 v[102:105], v[46:49], v[144:147], v[102:105]
	ds_read_b128 v[140:143], v191 offset:41216
	ds_read_b128 v[144:147], v191 offset:41280
	v_mfma_f32_16x16x32_bf16 v[106:109], v[14:17], v[148:151], v[106:109]
	v_mfma_f32_16x16x32_bf16 v[114:117], v[46:49], v[148:151], v[114:117]
	s_waitcnt lgkmcnt(1)
	v_mfma_f32_16x16x32_bf16 v[110:113], v[18:21], v[140:143], v[110:113]
	v_mfma_f32_16x16x32_bf16 v[140:143], v[50:53], v[140:143], v[102:105]
	s_nop 2
	ds_read_b128 v[102:105], v191 offset:49664
	ds_read_b128 v[148:151], v191 offset:49728
	v_mfma_f32_16x16x32_bf16 v[118:121], v[14:17], v[152:155], v[118:121]
	v_mfma_f32_16x16x32_bf16 v[122:125], v[46:49], v[152:155], v[122:125]
	v_mfma_f32_16x16x32_bf16 v[126:129], v[14:17], v[196:199], v[126:129]
	v_mfma_f32_16x16x32_bf16 v[136:139], v[46:49], v[196:199], v[136:139]
	s_waitcnt lgkmcnt(1)
	v_mfma_f32_16x16x32_bf16 v[152:155], v[18:21], v[102:105], v[106:109]
	v_mfma_f32_16x16x32_bf16 v[114:117], v[50:53], v[102:105], v[114:117]
	ds_read_b128 v[102:105], v191 offset:58112
	ds_read_b128 v[196:199], v191 offset:58176
	global_load_dwordx4 v[106:109], v[134:135], off
	ds_read_b128 v[200:203], v192 offset:41216
	ds_read_b128 v[204:207], v192 offset:41280
	s_waitcnt lgkmcnt(3)
	v_mfma_f32_16x16x32_bf16 v[118:121], v[18:21], v[102:105], v[118:121]
	v_mfma_f32_16x16x32_bf16 v[122:125], v[50:53], v[102:105], v[122:125]
	global_load_dwordx4 v[102:105], v[134:135], off offset:16
	ds_read_b128 v[208:211], v191 offset:41344
	ds_read_b128 v[212:215], v191 offset:41408
	v_mfma_f32_16x16x32_bf16 v[110:113], v[22:25], v[144:147], v[110:113]
	s_waitcnt lgkmcnt(1)
; __host__ __device__ __forceinline__ size_t img_off(int r, int c, int K) { return ((size_t)(r >> 7) * (size_t)(K >> 6) + (size_t)(c >> 6)) * 8192u + (size_t)(lds_byte(r & 127, c & 63) >> 1); }
; __device__ __forceinline__ unsigned cvt_pk_bf16(float lo, float hi) { unsigned r; asm volatile("v_cvt_pk_bf16_f32 %0, %1, %2" : "=v"(r) : "v"(lo), "v"(hi)); return r; }
; #define LAS __attribute__((address_space(3)))
; __device__ __forceinline__ float bf_lo(unsigned u) { return __uint_as_float(u << 16); }
; __device__ __forceinline__ float bf_hi(unsigned u) { return __uint_as_float(u & 0xffff0000u); }
; __device__ __forceinline__ void pool_phase(LAS unsigned char* lds, const bf16_t* PROJ, const bf16_t* PW, const float* pscale, bf16_t* Y, float* SS, int bx, int G) {
;     ...
;           for (int ks = 0; ks < 8; ++ks) {
;               if (ks + 1 < 8) {
; #pragma unroll
;                   for (int m = 0; m < 4; ++m) dfb[(ks + 1) & 1][m] = *(const LAS bf16x8*)(lds + PL_DT + (16 * m + fr) * PL_DROW + (32 * (ks + 1) + 8 * fq) * 2); }
; #pragma unroll
;               for (int m = 0; m < 4; ++m)
; #pragma unroll
;                   for (int j = 0; j < 2; ++j) acc[j][m] = MFMA16(wf[j][ks], dfb[ks & 1][m], acc[j][m]);
;           } }
;         const int cb = g * 256 + 32 * wid + 8 * fq; const f32x4 sc0 = *(const f32x4*)(pscale + cb), sc1 = *(const f32x4*)(pscale + cb + 4);
; #pragma unroll
;         for (int m = 0; m < 4; ++m) { const int tok = T0 + 16 * m + fr; float ssq = 0.f; const u32x4 gq = gt[m];
;             const float v0 = acc[0][m][0] * sc0[0] * bf_lo(gq.x), v1 = acc[0][m][1] * sc0[1] * bf_hi(gq.x), v2 = acc[0][m][2] * sc0[2] * bf_lo(gq.y), v3 = acc[0][m][3] * sc0[3] * bf_hi(gq.y);
;             const float v4 = acc[1][m][0] * sc1[0] * bf_lo(gq.z), v5 = acc[1][m][1] * sc1[1] * bf_hi(gq.z), v6 = acc[1][m][2] * sc1[2] * bf_lo(gq.w), v7 = acc[1][m][3] * sc1[3] * bf_hi(gq.w);
;             ssq = ((v0 * v0 + v1 * v1) + (v2 * v2 + v3 * v3)) + ((v4 * v4 + v5 * v5) + (v6 * v6 + v7 * v7));
;             u32x4 o; o.x = cvt_pk_bf16(v0, v1); o.y = cvt_pk_bf16(v2, v3); o.z = cvt_pk_bf16(v4, v5); o.w = cvt_pk_bf16(v6, v7); *(u32x4*)(Y + pg8::img_off(tok, cb, MIXW)) = o;
;             ssq += __shfl_xor(ssq, 16); ssq += __shfl_xor(ssq, 32);
;             if (fq == 0) ssw[wid * 64 + 16 * m + fr] = ssq; }
	v_mfma_f32_16x16x32_bf16 v[110:113], v[26:29], v[208:211], v[110:113]
	v_mfma_f32_16x16x32_bf16 v[140:143], v[54:57], v[144:147], v[140:143]
	s_waitcnt lgkmcnt(0)
	v_mfma_f32_16x16x32_bf16 v[110:113], v[30:33], v[212:215], v[110:113]
	v_mfma_f32_16x16x32_bf16 v[140:143], v[58:61], v[208:211], v[140:143]
	v_mfma_f32_16x16x32_bf16 v[144:147], v[22:25], v[148:151], v[152:155]
	s_waitcnt vmcnt(1)
	s_nop 4
	v_mul_f32_e32 v110, v110, v106
	v_mul_f32_e32 v152, v110, v181
	v_mul_f32_e32 v110, v111, v107
	v_mfma_f32_16x16x32_bf16 v[114:117], v[54:57], v[148:151], v[114:117]
	v_mul_f32_e32 v148, v110, v98
	v_mul_f32_e32 v98, v112, v108
	v_lshlrev_b32_e32 v110, 16, v99
	v_mul_f32_e32 v149, v98, v110
	v_mul_f32_e32 v98, v113, v109
	v_mfma_f32_16x16x32_bf16 v[110:113], v[62:65], v[212:215], v[140:143]
	v_and_b32_e32 v99, 0xffff0000, v99
	v_mfma_f32_16x16x32_bf16 v[126:129], v[18:21], v[200:203], v[126:129]
	s_nop 0
	v_mul_f32_e32 v143, v98, v99
	s_waitcnt vmcnt(0)
	s_nop 2
	v_mul_f32_e32 v98, v110, v102
	v_lshlrev_b32_e32 v99, 16, v100
	v_mfma_f32_16x16x32_bf16 v[136:139], v[50:53], v[200:203], v[136:139]
	ds_read_b128 v[200:203], v191 offset:49792
	ds_read_b128 v[216:219], v191 offset:49856
	ds_read_b128 v[220:223], v191 offset:58240
	ds_read_b128 v[224:227], v191 offset:58304
	v_mul_f32_e32 v150, v98, v99
	v_mul_f32_e32 v98, v111, v103
	v_and_b32_e32 v99, 0xffff0000, v100
	v_mul_f32_e32 v151, v98, v99
	v_mul_f32_e32 v98, v112, v104
	v_lshlrev_b32_e32 v99, 16, v101
	v_mul_f32_e32 v110, v113, v105
	v_and_b32_e32 v111, 0xffff0000, v101
	ds_read_b128 v[228:231], v192 offset:41344
	ds_read_b128 v[232:235], v192 offset:41408
	v_mfma_f32_16x16x32_bf16 v[126:129], v[22:25], v[204:207], v[126:129]
	v_mul_f32_e32 v153, v98, v99
	v_cvt_pk_bf16_f32 v142, v152, v148
	v_mfma_f32_16x16x32_bf16 v[98:101], v[54:57], v[204:207], v[136:139]
	s_nop 2
	v_mul_f32_e32 v136, v110, v111
	s_waitcnt lgkmcnt(5)
	v_mfma_f32_16x16x32_bf16 v[110:113], v[26:29], v[200:203], v[144:147]
	v_mul_f32_e32 v137, v148, v148
	v_mul_f32_e32 v138, v143, v143
	v_fmac_f32_e32 v137, v152, v152
	v_fmac_f32_e32 v138, v149, v149
	v_mul_f32_e32 v139, v136, v136
	v_cvt_pk_bf16_f32 v143, v149, v143
	s_waitcnt lgkmcnt(1)
	v_mfma_f32_16x16x32_bf16 v[146:149], v[26:29], v[228:231], v[126:129]
	v_add_f32_e32 v137, v137, v138
	v_mul_f32_e32 v138, v151, v151
	v_fmac_f32_e32 v139, v153, v153
	v_mfma_f32_16x16x32_bf16 v[126:129], v[30:33], v[216:219], v[110:113]
	v_cvt_pk_bf16_f32 v144, v150, v151
	v_cvt_pk_bf16_f32 v145, v153, v136
	v_fmac_f32_e32 v138, v150, v150
	v_mfma_f32_16x16x32_bf16 v[122:125], v[54:57], v[196:199], v[122:125]
	v_add_f32_e32 v138, v138, v139
	v_and_b32_e32 v111, 64, v193
	v_xor_b32_e32 v110, 16, v193
	v_add_u32_e32 v153, 64, v111
	v_cmp_lt_i32_e32 vcc, v110, v153
	v_add_f32_e32 v137, v137, v138
	v_mfma_f32_16x16x32_bf16 v[114:117], v[58:61], v[200:203], v[114:117]
	v_cndmask_b32_e32 v110, v193, v110, vcc
	v_lshlrev_b32_e32 v136, 2, v110
	ds_bpermute_b32 v110, v136, v137
	v_mfma_f32_16x16x32_bf16 v[138:141], v[58:61], v[220:223], v[122:125]
	v_lshrrev_b32_e32 v152, 4, v182
	v_and_or_b32 v150, v182, s87, v157
	v_and_b32_e32 v111, 32, v152
	v_mfma_f32_16x16x32_bf16 v[118:121], v[22:25], v[196:199], v[118:121]
	v_and_or_b32 v122, s72, 8, v156
	v_lshlrev_b32_e32 v151, 10, v122
	v_bitop3_b32 v111, v150, v151, v111 bitop3:0xde
	v_mfma_f32_16x16x32_bf16 v[122:125], v[62:65], v[216:219], v[114:117]
	global_store_dwordx4 v111, v[142:145], s[70:71]
	v_mfma_f32_16x16x32_bf16 v[114:117], v[62:65], v[224:227], v[138:141]
	s_waitcnt lgkmcnt(0)
	s_nop 1
	v_add_f32_e32 v138, v137, v110
	v_xor_b32_e32 v137, 32, v193
	v_mfma_f32_16x16x32_bf16 v[118:121], v[26:29], v[220:223], v[118:121]
	v_cmp_lt_i32_e32 vcc, v137, v153
	v_mfma_f32_16x16x32_bf16 v[98:101], v[58:61], v[228:231], v[98:101]
	s_nop 0
	v_cndmask_b32_e32 v137, v193, v137, vcc
	v_lshlrev_b32_e32 v137, 2, v137
	ds_bpermute_b32 v139, v137, v138
	v_mfma_f32_16x16x32_bf16 v[118:121], v[30:33], v[224:227], v[118:121]
	v_mfma_f32_16x16x32_bf16 v[110:113], v[30:33], v[232:235], v[146:149]
	v_mfma_f32_16x16x32_bf16 v[98:101], v[62:65], v[232:235], v[98:101]
	s_and_saveexec_b64 s[72:73], s[16:17]
	s_cbranch_execz .LBB0_621
	s_waitcnt lgkmcnt(0)
	v_add_f32_e32 v138, v138, v139
	ds_write_b32 v158, v138
